# plus in-proj sigmoid and q/k-norm epilogues: next row rstd loads issued before current row stores, counted vmcnt
# speedup vs baseline: 1.0045x; 1.0008x over previous
.LBB0_174:
	s_cmp_gt_i32 s16, 7
	s_mov_b64 s[42:43], -1
	s_cbranch_scc0 .LBB0_196
	s_add_i32 s17, s16, -12
	s_cmp_gt_u32 s17, 15
	s_cbranch_scc0 .LBB0_177
	v_ashrrev_i32_e32 v171, 31, v170
	v_lshlrev_b64 v[134:135], 6, v[170:171]
	v_lshl_add_u64 v[146:147], s[92:93], 0, v[134:135]
	global_load_dwordx4 v[134:137], v[146:147], off offset:32
	global_load_dwordx4 v[138:141], v[146:147], off offset:48
	global_load_dwordx4 v[142:145], v[146:147], off
	s_nop 0
	global_load_dwordx4 v[146:149], v[146:147], off offset:16
	s_cmp_lt_u32 s16, 12
	s_cselect_b64 vcc, -1, 0
	s_cmp_lt_u32 s16, 32
	s_mov_b32 s17, 0x18c00000
	s_cselect_b32 s17, s17, 0x1ac00000
	s_and_b64 s[42:43], vcc, exec
	s_cselect_b32 s17, 0x12c00000, s17
	s_add_u32 s42, s38, s17
	s_addc_u32 s43, s39, 0
	s_add_i32 s17, s16, -8
	s_and_b32 s22, s16, 3
	s_and_b64 s[46:47], vcc, exec
	s_cselect_b32 s17, s17, s22
	v_lshlrev_b32_e32 v0, 1, v222
	v_lshl_or_b32 v0, s17, 9, v0
	v_lshl_add_u64 v[130:131], s[42:43], 0, v[0:1]
	v_lshlrev_b64 v[132:133], 11, v[170:171]
	v_lshl_add_u64 v[132:133], v[130:131], 0, v[132:133]
	s_mov_b64 s[42:43], 0
	s_waitcnt vmcnt(0)
	v_pk_add_f32 v[136:137], v[136:137], v[140:141]
	v_pk_add_f32 v[134:135], v[134:135], v[138:139]
	v_pk_add_f32 v[144:145], v[144:145], v[148:149]
	v_pk_add_f32 v[142:143], v[142:143], v[146:147]
	v_or_b32_e32 v202, 16, v170
	v_ashrrev_i32_e32 v203, 31, v202
	v_lshlrev_b64 v[202:203], 6, v[202:203]
	v_lshl_add_u64 v[204:205], s[92:93], 0, v[202:203]
	global_load_dwordx4 v[186:189], v[204:205], off offset:32
	global_load_dwordx4 v[190:193], v[204:205], off offset:48
	global_load_dwordx4 v[194:197], v[204:205], off
	global_load_dwordx4 v[198:201], v[204:205], off offset:16
	v_pk_add_f32 v[136:137], v[144:145], v[136:137]
	v_pk_add_f32 v[134:135], v[142:143], v[134:135]
	s_nop 0
	v_pk_mov_b32 v[138:139], v[134:135], v[136:137] op_sel:[1,0]
	v_mov_b32_e32 v135, v137
	v_pk_add_f32 v[134:135], v[138:139], v[134:135]
	s_nop 0
	v_add_f32_e32 v0, v134, v135
	v_fmamk_f32 v0, v0, 0x3a800000, v211
	v_rsq_f32_e32 v0, v0
	s_nop 0
	v_pk_mul_f32 v[136:137], v[126:127], v[0:1] op_sel_hi:[1,0]
	v_pk_mul_f32 v[140:141], v[122:123], v[0:1] op_sel_hi:[1,0]
	v_mul_f32_e32 v142, 0xbfb8aa3b, v136
	v_exp_f32_e32 v142, v142
	v_mul_f32_e32 v143, 0xbfb8aa3b, v140
	v_exp_f32_e32 v143, v143
	v_pk_mul_f32 v[134:135], v[128:129], v[0:1] op_sel_hi:[1,0]
	v_add_f32_e32 v142, 1.0, v142
	v_rcp_f32_e32 v142, v142
	v_add_f32_e32 v143, 1.0, v143
	v_rcp_f32_e32 v143, v143
	v_pk_mul_f32 v[138:139], v[124:125], v[0:1] op_sel_hi:[1,0]
	v_mul_f32_e32 v136, v136, v142
	v_cndmask_b32_e32 v136, v142, v136, vcc
	v_mul_f32_e32 v140, v140, v143
	v_mul_f32_e32 v142, 0xbfb8aa3b, v137
	v_cndmask_b32_e32 v140, v143, v140, vcc
	v_exp_f32_e32 v142, v142
	v_mul_f32_e32 v143, 0xbfb8aa3b, v141
	v_exp_f32_e32 v143, v143
	v_add_f32_e32 v142, 1.0, v142
	v_rcp_f32_e32 v142, v142
	v_add_f32_e32 v143, 1.0, v143
	v_rcp_f32_e32 v143, v143
	v_mul_f32_e32 v137, v137, v142
	v_cndmask_b32_e32 v137, v142, v137, vcc
	v_mul_f32_e32 v141, v141, v143
	v_mul_f32_e32 v142, 0xbfb8aa3b, v134
	v_cndmask_b32_e32 v141, v143, v141, vcc
	v_exp_f32_e32 v142, v142
	v_mul_f32_e32 v143, 0xbfb8aa3b, v138
	v_exp_f32_e32 v143, v143
	v_add_f32_e32 v142, 1.0, v142
	v_rcp_f32_e32 v142, v142
	v_add_f32_e32 v143, 1.0, v143
	v_rcp_f32_e32 v143, v143
	v_mul_f32_e32 v134, v134, v142
	v_cndmask_b32_e32 v142, v142, v134, vcc
	v_mul_f32_e32 v134, v138, v143
	v_cndmask_b32_e32 v138, v143, v134, vcc
	v_mul_f32_e32 v134, 0xbfb8aa3b, v135
	v_exp_f32_e32 v134, v134
	v_mul_f32_e32 v143, 0xbfb8aa3b, v139
	v_exp_f32_e32 v143, v143
	v_add_f32_e32 v134, 1.0, v134
	v_rcp_f32_e32 v134, v134
	v_add_f32_e32 v143, 1.0, v143
	v_rcp_f32_e32 v143, v143
	v_mul_f32_e32 v135, v135, v134
	v_cndmask_b32_e32 v135, v134, v135, vcc
	v_mul_f32_e32 v134, v139, v143
	v_cndmask_b32_e32 v139, v143, v134, vcc
	v_cvt_pk_bf16_f32 v134, v136, v137
	v_cvt_pk_bf16_f32 v135, v142, v135
	v_cvt_pk_bf16_f32 v136, v140, v141
	v_cvt_pk_bf16_f32 v137, v138, v139
	v_pk_mul_f32 v[138:139], v[118:119], v[0:1] op_sel_hi:[1,0]
	global_store_dwordx4 v[132:133], v[134:137], off
	v_pk_mul_f32 v[140:141], v[110:111], v[0:1] op_sel_hi:[1,0]
	s_nop 0
	v_pk_mul_f32 v[134:135], v[120:121], v[0:1] op_sel_hi:[1,0]
	v_pk_mul_f32 v[136:137], v[112:113], v[0:1] op_sel_hi:[1,0]
	v_mul_f32_e32 v0, 0xbfb8aa3b, v138
	v_exp_f32_e32 v0, v0
	v_mul_f32_e32 v142, 0xbfb8aa3b, v140
	v_exp_f32_e32 v142, v142
	v_add_f32_e32 v0, 1.0, v0
	v_rcp_f32_e32 v0, v0
	v_add_f32_e32 v142, 1.0, v142
	v_rcp_f32_e32 v142, v142
	v_mul_f32_e32 v138, v138, v0
	v_cndmask_b32_e32 v0, v0, v138, vcc
	v_mul_f32_e32 v138, v140, v142
	v_mul_f32_e32 v140, 0xbfb8aa3b, v139
	v_cndmask_b32_e32 v138, v142, v138, vcc
	v_exp_f32_e32 v140, v140
	v_mul_f32_e32 v142, 0xbfb8aa3b, v141
	v_exp_f32_e32 v142, v142
	v_add_f32_e32 v140, 1.0, v140
	v_rcp_f32_e32 v140, v140
	v_add_f32_e32 v142, 1.0, v142
	v_rcp_f32_e32 v142, v142
	v_mul_f32_e32 v139, v139, v140
	v_cndmask_b32_e32 v139, v140, v139, vcc
	v_mul_f32_e32 v140, v141, v142
	v_mul_f32_e32 v141, 0xbfb8aa3b, v134
	v_cndmask_b32_e32 v140, v142, v140, vcc
	v_exp_f32_e32 v141, v141
	v_mul_f32_e32 v142, 0xbfb8aa3b, v136
	v_exp_f32_e32 v142, v142
	v_add_f32_e32 v141, 1.0, v141
	v_rcp_f32_e32 v141, v141
	v_add_f32_e32 v142, 1.0, v142
	v_rcp_f32_e32 v142, v142
	v_mul_f32_e32 v134, v134, v141
	v_cndmask_b32_e32 v141, v141, v134, vcc
	v_mul_f32_e32 v134, v136, v142
	v_cndmask_b32_e32 v142, v142, v134, vcc
	v_mul_f32_e32 v134, 0xbfb8aa3b, v135
	v_exp_f32_e32 v134, v134
	v_mul_f32_e32 v136, 0xbfb8aa3b, v137
	v_exp_f32_e32 v136, v136
	v_add_f32_e32 v134, 1.0, v134
	v_rcp_f32_e32 v134, v134
	v_add_f32_e32 v136, 1.0, v136
	v_rcp_f32_e32 v136, v136
	v_mul_f32_e32 v135, v135, v134
	v_cndmask_b32_e32 v135, v134, v135, vcc
	v_mul_f32_e32 v134, v137, v136
	v_cndmask_b32_e32 v137, v136, v134, vcc
	v_cvt_pk_bf16_f32 v134, v0, v139
	v_cvt_pk_bf16_f32 v135, v141, v135
	v_cvt_pk_bf16_f32 v136, v138, v140
	v_cvt_pk_bf16_f32 v137, v142, v137
	global_store_dwordx4 v[132:133], v[134:137], off offset:64
	s_nop 1
	v_or_b32_e32 v134, 16, v170
	v_ashrrev_i32_e32 v135, 31, v134
	v_lshlrev_b64 v[132:133], 11, v[134:135]
	v_lshl_add_u64 v[132:133], v[130:131], 0, v[132:133]
	s_waitcnt vmcnt(2)
	v_pk_add_f32 v[136:137], v[188:189], v[192:193]
	v_pk_add_f32 v[134:135], v[186:187], v[190:191]
	v_pk_add_f32 v[144:145], v[196:197], v[200:201]
	v_pk_add_f32 v[142:143], v[194:195], v[198:199]
	v_or_b32_e32 v202, 32, v170
	v_ashrrev_i32_e32 v203, 31, v202
	v_lshlrev_b64 v[202:203], 6, v[202:203]
	v_lshl_add_u64 v[204:205], s[92:93], 0, v[202:203]
	global_load_dwordx4 v[186:189], v[204:205], off offset:32
	global_load_dwordx4 v[190:193], v[204:205], off offset:48
	global_load_dwordx4 v[194:197], v[204:205], off
	global_load_dwordx4 v[198:201], v[204:205], off offset:16
	v_pk_add_f32 v[136:137], v[144:145], v[136:137]
	v_pk_add_f32 v[134:135], v[142:143], v[134:135]
	s_nop 0
	v_pk_mov_b32 v[138:139], v[134:135], v[136:137] op_sel:[1,0]
	v_mov_b32_e32 v135, v137
	v_pk_add_f32 v[134:135], v[138:139], v[134:135]
	s_nop 0
	v_add_f32_e32 v0, v134, v135
	v_fmamk_f32 v0, v0, 0x3a800000, v211
	v_rsq_f32_e32 v0, v0
	s_nop 0
	v_pk_mul_f32 v[138:139], v[114:115], v[0:1] op_sel_hi:[1,0]
	v_pk_mul_f32 v[140:141], v[106:107], v[0:1] op_sel_hi:[1,0]
	v_mul_f32_e32 v142, 0xbfb8aa3b, v138
	v_exp_f32_e32 v142, v142
	v_mul_f32_e32 v143, 0xbfb8aa3b, v140
	v_exp_f32_e32 v143, v143
	v_pk_mul_f32 v[134:135], v[116:117], v[0:1] op_sel_hi:[1,0]
	v_add_f32_e32 v142, 1.0, v142
	v_rcp_f32_e32 v142, v142
	v_add_f32_e32 v143, 1.0, v143
	v_rcp_f32_e32 v143, v143
	v_pk_mul_f32 v[136:137], v[108:109], v[0:1] op_sel_hi:[1,0]
	v_mul_f32_e32 v138, v138, v142
	v_cndmask_b32_e32 v138, v142, v138, vcc
	v_mul_f32_e32 v140, v140, v143
	v_mul_f32_e32 v142, 0xbfb8aa3b, v139
	v_cndmask_b32_e32 v140, v143, v140, vcc
	v_exp_f32_e32 v142, v142
	v_mul_f32_e32 v143, 0xbfb8aa3b, v141
	v_exp_f32_e32 v143, v143
	v_add_f32_e32 v142, 1.0, v142
	v_rcp_f32_e32 v142, v142
	v_add_f32_e32 v143, 1.0, v143
	v_rcp_f32_e32 v143, v143
	v_mul_f32_e32 v139, v139, v142
	v_cndmask_b32_e32 v139, v142, v139, vcc
	v_mul_f32_e32 v141, v141, v143
	v_mul_f32_e32 v142, 0xbfb8aa3b, v134
	v_cndmask_b32_e32 v141, v143, v141, vcc
	v_exp_f32_e32 v142, v142
	v_mul_f32_e32 v143, 0xbfb8aa3b, v136
	v_exp_f32_e32 v143, v143
	v_add_f32_e32 v142, 1.0, v142
	v_rcp_f32_e32 v142, v142
	v_add_f32_e32 v143, 1.0, v143
	v_rcp_f32_e32 v143, v143
	v_mul_f32_e32 v134, v134, v142
	v_cndmask_b32_e32 v142, v142, v134, vcc
	v_mul_f32_e32 v134, v136, v143
	v_cndmask_b32_e32 v143, v143, v134, vcc
	v_mul_f32_e32 v134, 0xbfb8aa3b, v135
	v_exp_f32_e32 v134, v134
	v_mul_f32_e32 v136, 0xbfb8aa3b, v137
	v_exp_f32_e32 v136, v136
	v_add_f32_e32 v134, 1.0, v134
	v_rcp_f32_e32 v134, v134
	v_add_f32_e32 v136, 1.0, v136
	v_rcp_f32_e32 v136, v136
	v_mul_f32_e32 v135, v135, v134
	v_cndmask_b32_e32 v135, v134, v135, vcc
	v_mul_f32_e32 v134, v137, v136
	v_cndmask_b32_e32 v137, v136, v134, vcc
	v_cvt_pk_bf16_f32 v134, v138, v139
	v_cvt_pk_bf16_f32 v135, v142, v135
	v_cvt_pk_bf16_f32 v136, v140, v141
	v_cvt_pk_bf16_f32 v137, v143, v137
	global_store_dwordx4 v[132:133], v[134:137], off
	v_pk_mul_f32 v[138:139], v[96:97], v[0:1] op_sel_hi:[1,0]
	v_pk_mul_f32 v[140:141], v[94:95], v[0:1] op_sel_hi:[1,0]
	v_pk_mul_f32 v[136:137], v[102:103], v[0:1] op_sel_hi:[1,0]
	v_pk_mul_f32 v[134:135], v[104:105], v[0:1] op_sel_hi:[1,0]
	v_mul_f32_e32 v0, 0xbfb8aa3b, v136
	v_exp_f32_e32 v0, v0
	v_mul_f32_e32 v142, 0xbfb8aa3b, v140
	v_exp_f32_e32 v142, v142
	v_add_f32_e32 v0, 1.0, v0
	v_rcp_f32_e32 v0, v0
	v_add_f32_e32 v142, 1.0, v142
	v_rcp_f32_e32 v142, v142
	v_mul_f32_e32 v136, v136, v0
	v_cndmask_b32_e32 v0, v0, v136, vcc
	v_mul_f32_e32 v136, v140, v142
	v_mul_f32_e32 v140, 0xbfb8aa3b, v137
	v_cndmask_b32_e32 v136, v142, v136, vcc
	v_exp_f32_e32 v140, v140
	v_mul_f32_e32 v142, 0xbfb8aa3b, v141
	v_exp_f32_e32 v142, v142
	v_add_f32_e32 v140, 1.0, v140
	v_rcp_f32_e32 v140, v140
	v_add_f32_e32 v142, 1.0, v142
	v_rcp_f32_e32 v142, v142
	v_mul_f32_e32 v137, v137, v140
	v_cndmask_b32_e32 v137, v140, v137, vcc
	v_mul_f32_e32 v140, v141, v142
	v_mul_f32_e32 v141, 0xbfb8aa3b, v134
	v_cndmask_b32_e32 v140, v142, v140, vcc
	v_exp_f32_e32 v141, v141
	v_mul_f32_e32 v142, 0xbfb8aa3b, v138
	v_exp_f32_e32 v142, v142
	v_add_f32_e32 v141, 1.0, v141
	v_rcp_f32_e32 v141, v141
	v_add_f32_e32 v142, 1.0, v142
	v_rcp_f32_e32 v142, v142
	v_mul_f32_e32 v134, v134, v141
	v_cndmask_b32_e32 v141, v141, v134, vcc
	v_mul_f32_e32 v134, v138, v142
	v_cndmask_b32_e32 v138, v142, v134, vcc
	v_mul_f32_e32 v134, 0xbfb8aa3b, v135
	v_exp_f32_e32 v134, v134
	v_mul_f32_e32 v142, 0xbfb8aa3b, v139
	v_exp_f32_e32 v142, v142
	v_add_f32_e32 v134, 1.0, v134
	v_rcp_f32_e32 v134, v134
	v_add_f32_e32 v142, 1.0, v142
	v_rcp_f32_e32 v142, v142
	v_mul_f32_e32 v135, v135, v134
	v_cndmask_b32_e32 v135, v134, v135, vcc
	v_mul_f32_e32 v134, v139, v142
	v_cndmask_b32_e32 v139, v142, v134, vcc
	v_cvt_pk_bf16_f32 v134, v0, v137
	v_cvt_pk_bf16_f32 v135, v141, v135
	v_cvt_pk_bf16_f32 v136, v136, v140
	v_cvt_pk_bf16_f32 v137, v138, v139
	global_store_dwordx4 v[132:133], v[134:137], off offset:64
	s_nop 1
	v_or_b32_e32 v134, 32, v170
	v_ashrrev_i32_e32 v135, 31, v134
	v_lshlrev_b64 v[132:133], 11, v[134:135]
	v_lshl_add_u64 v[132:133], v[130:131], 0, v[132:133]
	s_waitcnt vmcnt(2)
	v_pk_add_f32 v[136:137], v[188:189], v[192:193]
	v_pk_add_f32 v[134:135], v[186:187], v[190:191]
	v_pk_add_f32 v[144:145], v[196:197], v[200:201]
	v_pk_add_f32 v[142:143], v[194:195], v[198:199]
	v_or_b32_e32 v202, 48, v170
	v_ashrrev_i32_e32 v203, 31, v202
	v_lshlrev_b64 v[202:203], 6, v[202:203]
	v_lshl_add_u64 v[204:205], s[92:93], 0, v[202:203]
	global_load_dwordx4 v[186:189], v[204:205], off offset:32
	global_load_dwordx4 v[190:193], v[204:205], off offset:48
	global_load_dwordx4 v[194:197], v[204:205], off
	global_load_dwordx4 v[198:201], v[204:205], off offset:16
	v_pk_add_f32 v[136:137], v[144:145], v[136:137]
	v_pk_add_f32 v[134:135], v[142:143], v[134:135]
	s_nop 0
	v_pk_mov_b32 v[138:139], v[134:135], v[136:137] op_sel:[1,0]
	v_mov_b32_e32 v135, v137
	v_pk_add_f32 v[134:135], v[138:139], v[134:135]
	s_nop 0
	v_add_f32_e32 v0, v134, v135
	v_fmamk_f32 v0, v0, 0x3a800000, v211
	v_rsq_f32_e32 v0, v0
	s_nop 0
	v_pk_mul_f32 v[136:137], v[98:99], v[0:1] op_sel_hi:[1,0]
	v_pk_mul_f32 v[140:141], v[90:91], v[0:1] op_sel_hi:[1,0]
	v_mul_f32_e32 v142, 0xbfb8aa3b, v136
	v_exp_f32_e32 v142, v142
	v_mul_f32_e32 v143, 0xbfb8aa3b, v140
	v_exp_f32_e32 v143, v143
	v_pk_mul_f32 v[134:135], v[100:101], v[0:1] op_sel_hi:[1,0]
	v_add_f32_e32 v142, 1.0, v142
	v_rcp_f32_e32 v142, v142
	v_add_f32_e32 v143, 1.0, v143
	v_rcp_f32_e32 v143, v143
	v_pk_mul_f32 v[138:139], v[92:93], v[0:1] op_sel_hi:[1,0]
	v_mul_f32_e32 v136, v136, v142
	v_cndmask_b32_e32 v136, v142, v136, vcc
	v_mul_f32_e32 v140, v140, v143
	v_mul_f32_e32 v142, 0xbfb8aa3b, v137
	v_cndmask_b32_e32 v140, v143, v140, vcc
	v_exp_f32_e32 v142, v142
	v_mul_f32_e32 v143, 0xbfb8aa3b, v141
	v_exp_f32_e32 v143, v143
	v_add_f32_e32 v142, 1.0, v142
	v_rcp_f32_e32 v142, v142
	v_add_f32_e32 v143, 1.0, v143
	v_rcp_f32_e32 v143, v143
	v_mul_f32_e32 v137, v137, v142
	v_cndmask_b32_e32 v137, v142, v137, vcc
	v_mul_f32_e32 v141, v141, v143
	v_mul_f32_e32 v142, 0xbfb8aa3b, v134
	v_cndmask_b32_e32 v141, v143, v141, vcc
	v_exp_f32_e32 v142, v142
	v_mul_f32_e32 v143, 0xbfb8aa3b, v138
	v_exp_f32_e32 v143, v143
	v_add_f32_e32 v142, 1.0, v142
	v_rcp_f32_e32 v142, v142
	v_add_f32_e32 v143, 1.0, v143
	v_rcp_f32_e32 v143, v143
	v_mul_f32_e32 v134, v134, v142
	v_cndmask_b32_e32 v142, v142, v134, vcc
	v_mul_f32_e32 v134, v138, v143
	v_cndmask_b32_e32 v138, v143, v134, vcc
	v_mul_f32_e32 v134, 0xbfb8aa3b, v135
	v_exp_f32_e32 v134, v134
	v_mul_f32_e32 v143, 0xbfb8aa3b, v139
	v_exp_f32_e32 v143, v143
	v_add_f32_e32 v134, 1.0, v134
	v_rcp_f32_e32 v134, v134
	v_add_f32_e32 v143, 1.0, v143
	v_rcp_f32_e32 v143, v143
	v_mul_f32_e32 v135, v135, v134
	v_cndmask_b32_e32 v135, v134, v135, vcc
	v_mul_f32_e32 v134, v139, v143
	v_cndmask_b32_e32 v139, v143, v134, vcc
	v_cvt_pk_bf16_f32 v134, v136, v137
	v_cvt_pk_bf16_f32 v135, v142, v135
	v_cvt_pk_bf16_f32 v136, v140, v141
	v_cvt_pk_bf16_f32 v137, v138, v139
	global_store_dwordx4 v[132:133], v[134:137], off
	v_pk_mul_f32 v[138:139], v[80:81], v[0:1] op_sel_hi:[1,0]
	v_pk_mul_f32 v[140:141], v[78:79], v[0:1] op_sel_hi:[1,0]
	v_pk_mul_f32 v[136:137], v[86:87], v[0:1] op_sel_hi:[1,0]
	v_pk_mul_f32 v[134:135], v[88:89], v[0:1] op_sel_hi:[1,0]
	v_mul_f32_e32 v0, 0xbfb8aa3b, v136
	v_exp_f32_e32 v0, v0
	v_mul_f32_e32 v142, 0xbfb8aa3b, v140
	v_exp_f32_e32 v142, v142
	v_add_f32_e32 v0, 1.0, v0
	v_rcp_f32_e32 v0, v0
	v_add_f32_e32 v142, 1.0, v142
	v_rcp_f32_e32 v142, v142
	v_mul_f32_e32 v136, v136, v0
	v_cndmask_b32_e32 v0, v0, v136, vcc
	v_mul_f32_e32 v136, v140, v142
	v_mul_f32_e32 v140, 0xbfb8aa3b, v137
	v_cndmask_b32_e32 v136, v142, v136, vcc
	v_exp_f32_e32 v140, v140
	v_mul_f32_e32 v142, 0xbfb8aa3b, v141
	v_exp_f32_e32 v142, v142
	v_add_f32_e32 v140, 1.0, v140
	v_rcp_f32_e32 v140, v140
	v_add_f32_e32 v142, 1.0, v142
	v_rcp_f32_e32 v142, v142
	v_mul_f32_e32 v137, v137, v140
	v_cndmask_b32_e32 v137, v140, v137, vcc
	v_mul_f32_e32 v140, v141, v142
	v_mul_f32_e32 v141, 0xbfb8aa3b, v134
	v_cndmask_b32_e32 v140, v142, v140, vcc
	v_exp_f32_e32 v141, v141
	v_mul_f32_e32 v142, 0xbfb8aa3b, v138
	v_exp_f32_e32 v142, v142
	v_add_f32_e32 v141, 1.0, v141
	v_rcp_f32_e32 v141, v141
	v_add_f32_e32 v142, 1.0, v142
	v_rcp_f32_e32 v142, v142
	v_mul_f32_e32 v134, v134, v141
	v_cndmask_b32_e32 v141, v141, v134, vcc
	v_mul_f32_e32 v134, v138, v142
	v_cndmask_b32_e32 v138, v142, v134, vcc
	v_mul_f32_e32 v134, 0xbfb8aa3b, v135
	v_exp_f32_e32 v134, v134
	v_mul_f32_e32 v142, 0xbfb8aa3b, v139
	v_exp_f32_e32 v142, v142
	v_add_f32_e32 v134, 1.0, v134
	v_rcp_f32_e32 v134, v134
	v_add_f32_e32 v142, 1.0, v142
	v_rcp_f32_e32 v142, v142
	v_mul_f32_e32 v135, v135, v134
	v_cndmask_b32_e32 v135, v134, v135, vcc
	v_mul_f32_e32 v134, v139, v142
	v_cndmask_b32_e32 v139, v142, v134, vcc
	v_cvt_pk_bf16_f32 v134, v0, v137
	v_cvt_pk_bf16_f32 v135, v141, v135
	v_cvt_pk_bf16_f32 v136, v136, v140
	v_cvt_pk_bf16_f32 v137, v138, v139
	global_store_dwordx4 v[132:133], v[134:137], off offset:64
	s_nop 1
	v_or_b32_e32 v134, 48, v170
	v_ashrrev_i32_e32 v135, 31, v134
	v_lshlrev_b64 v[132:133], 11, v[134:135]
	v_lshl_add_u64 v[132:133], v[130:131], 0, v[132:133]
	s_waitcnt vmcnt(2)
	v_pk_add_f32 v[136:137], v[188:189], v[192:193]
	v_pk_add_f32 v[134:135], v[186:187], v[190:191]
	v_pk_add_f32 v[144:145], v[196:197], v[200:201]
	v_pk_add_f32 v[142:143], v[194:195], v[198:199]
	v_add_u32_e32 v202, 0x80, v170
	v_ashrrev_i32_e32 v203, 31, v202
	v_lshlrev_b64 v[202:203], 6, v[202:203]
	v_lshl_add_u64 v[204:205], s[92:93], 0, v[202:203]
	global_load_dwordx4 v[186:189], v[204:205], off offset:32
	global_load_dwordx4 v[190:193], v[204:205], off offset:48
	global_load_dwordx4 v[194:197], v[204:205], off
	global_load_dwordx4 v[198:201], v[204:205], off offset:16
	v_pk_add_f32 v[136:137], v[144:145], v[136:137]
	v_pk_add_f32 v[134:135], v[142:143], v[134:135]
	s_nop 0
	v_pk_mov_b32 v[138:139], v[134:135], v[136:137] op_sel:[1,0]
	v_mov_b32_e32 v135, v137
	v_pk_add_f32 v[134:135], v[138:139], v[134:135]
	s_nop 0
	v_add_f32_e32 v0, v134, v135
	v_fmamk_f32 v0, v0, 0x3a800000, v211
	v_rsq_f32_e32 v0, v0
	s_nop 0
	v_pk_mul_f32 v[136:137], v[82:83], v[0:1] op_sel_hi:[1,0]
	v_pk_mul_f32 v[140:141], v[74:75], v[0:1] op_sel_hi:[1,0]
	v_mul_f32_e32 v142, 0xbfb8aa3b, v136
	v_exp_f32_e32 v142, v142
	v_mul_f32_e32 v143, 0xbfb8aa3b, v140
	v_exp_f32_e32 v143, v143
	v_pk_mul_f32 v[134:135], v[84:85], v[0:1] op_sel_hi:[1,0]
	v_add_f32_e32 v142, 1.0, v142
	v_rcp_f32_e32 v142, v142
	v_add_f32_e32 v143, 1.0, v143
	v_rcp_f32_e32 v143, v143
	v_pk_mul_f32 v[138:139], v[76:77], v[0:1] op_sel_hi:[1,0]
	v_mul_f32_e32 v136, v136, v142
	v_cndmask_b32_e32 v136, v142, v136, vcc
	v_mul_f32_e32 v140, v140, v143
	v_mul_f32_e32 v142, 0xbfb8aa3b, v137
	v_cndmask_b32_e32 v140, v143, v140, vcc
	v_exp_f32_e32 v142, v142
	v_mul_f32_e32 v143, 0xbfb8aa3b, v141
	v_exp_f32_e32 v143, v143
	v_add_f32_e32 v142, 1.0, v142
	v_rcp_f32_e32 v142, v142
	v_add_f32_e32 v143, 1.0, v143
	v_rcp_f32_e32 v143, v143
	v_mul_f32_e32 v137, v137, v142
	v_cndmask_b32_e32 v137, v142, v137, vcc
	v_mul_f32_e32 v141, v141, v143
	v_mul_f32_e32 v142, 0xbfb8aa3b, v134
	v_cndmask_b32_e32 v141, v143, v141, vcc
	v_exp_f32_e32 v142, v142
	v_mul_f32_e32 v143, 0xbfb8aa3b, v138
	v_exp_f32_e32 v143, v143
	v_add_f32_e32 v142, 1.0, v142
	v_rcp_f32_e32 v142, v142
	v_add_f32_e32 v143, 1.0, v143
	v_rcp_f32_e32 v143, v143
	v_mul_f32_e32 v134, v134, v142
	v_cndmask_b32_e32 v142, v142, v134, vcc
	v_mul_f32_e32 v134, v138, v143
	v_cndmask_b32_e32 v138, v143, v134, vcc
	v_mul_f32_e32 v134, 0xbfb8aa3b, v135
	v_exp_f32_e32 v134, v134
	v_mul_f32_e32 v143, 0xbfb8aa3b, v139
	v_exp_f32_e32 v143, v143
	v_add_f32_e32 v134, 1.0, v134
	v_rcp_f32_e32 v134, v134
	v_add_f32_e32 v143, 1.0, v143
	v_rcp_f32_e32 v143, v143
	v_mul_f32_e32 v135, v135, v134
	v_cndmask_b32_e32 v135, v134, v135, vcc
	v_mul_f32_e32 v134, v139, v143
	v_cndmask_b32_e32 v139, v143, v134, vcc
	v_cvt_pk_bf16_f32 v134, v136, v137
	v_cvt_pk_bf16_f32 v135, v142, v135
	v_cvt_pk_bf16_f32 v136, v140, v141
	v_cvt_pk_bf16_f32 v137, v138, v139
	global_store_dwordx4 v[132:133], v[134:137], off
	v_pk_mul_f32 v[138:139], v[68:69], v[0:1] op_sel_hi:[1,0]
	v_pk_mul_f32 v[140:141], v[66:67], v[0:1] op_sel_hi:[1,0]
	v_pk_mul_f32 v[136:137], v[70:71], v[0:1] op_sel_hi:[1,0]
	v_pk_mul_f32 v[134:135], v[72:73], v[0:1] op_sel_hi:[1,0]
	v_mul_f32_e32 v0, 0xbfb8aa3b, v136
	v_exp_f32_e32 v0, v0
	v_mul_f32_e32 v142, 0xbfb8aa3b, v140
	v_exp_f32_e32 v142, v142
	v_add_f32_e32 v0, 1.0, v0
	v_rcp_f32_e32 v0, v0
	v_add_f32_e32 v142, 1.0, v142
	v_rcp_f32_e32 v142, v142
	v_mul_f32_e32 v136, v136, v0
	v_cndmask_b32_e32 v0, v0, v136, vcc
	v_mul_f32_e32 v136, v140, v142
	v_mul_f32_e32 v140, 0xbfb8aa3b, v137
	v_cndmask_b32_e32 v136, v142, v136, vcc
	v_exp_f32_e32 v140, v140
	v_mul_f32_e32 v142, 0xbfb8aa3b, v141
	v_exp_f32_e32 v142, v142
	v_add_f32_e32 v140, 1.0, v140
	v_rcp_f32_e32 v140, v140
	v_add_f32_e32 v142, 1.0, v142
	v_rcp_f32_e32 v142, v142
	v_mul_f32_e32 v137, v137, v140
	v_cndmask_b32_e32 v137, v140, v137, vcc
	v_mul_f32_e32 v140, v141, v142
	v_mul_f32_e32 v141, 0xbfb8aa3b, v134
	v_cndmask_b32_e32 v140, v142, v140, vcc
	v_exp_f32_e32 v141, v141
	v_mul_f32_e32 v142, 0xbfb8aa3b, v138
	v_exp_f32_e32 v142, v142
	v_add_f32_e32 v141, 1.0, v141
	v_rcp_f32_e32 v141, v141
	v_add_f32_e32 v142, 1.0, v142
	v_rcp_f32_e32 v142, v142
	v_mul_f32_e32 v134, v134, v141
	v_cndmask_b32_e32 v141, v141, v134, vcc
	v_mul_f32_e32 v134, v138, v142
	v_cndmask_b32_e32 v138, v142, v134, vcc
	v_mul_f32_e32 v134, 0xbfb8aa3b, v135
	v_exp_f32_e32 v134, v134
	v_mul_f32_e32 v142, 0xbfb8aa3b, v139
	v_exp_f32_e32 v142, v142
	v_add_f32_e32 v134, 1.0, v134
	v_rcp_f32_e32 v134, v134
	v_add_f32_e32 v142, 1.0, v142
	v_rcp_f32_e32 v142, v142
	v_mul_f32_e32 v135, v135, v134
	v_cndmask_b32_e32 v135, v134, v135, vcc
	v_mul_f32_e32 v134, v139, v142
	v_cndmask_b32_e32 v139, v142, v134, vcc
	v_cvt_pk_bf16_f32 v134, v0, v137
	v_cvt_pk_bf16_f32 v135, v141, v135
	v_cvt_pk_bf16_f32 v136, v136, v140
	v_cvt_pk_bf16_f32 v137, v138, v139
	global_store_dwordx4 v[132:133], v[134:137], off offset:64
	s_nop 1
	v_add_u32_e32 v134, 0x80, v170
	v_ashrrev_i32_e32 v135, 31, v134
	v_lshlrev_b64 v[132:133], 11, v[134:135]
	v_lshl_add_u64 v[132:133], v[130:131], 0, v[132:133]
	s_waitcnt vmcnt(2)
	v_pk_add_f32 v[136:137], v[188:189], v[192:193]
	v_pk_add_f32 v[134:135], v[186:187], v[190:191]
	v_pk_add_f32 v[144:145], v[196:197], v[200:201]
	v_pk_add_f32 v[142:143], v[194:195], v[198:199]
	v_add_u32_e32 v202, 0x90, v170
	v_ashrrev_i32_e32 v203, 31, v202
	v_lshlrev_b64 v[202:203], 6, v[202:203]
	v_lshl_add_u64 v[204:205], s[92:93], 0, v[202:203]
	global_load_dwordx4 v[186:189], v[204:205], off offset:32
	global_load_dwordx4 v[190:193], v[204:205], off offset:48
	global_load_dwordx4 v[194:197], v[204:205], off
	global_load_dwordx4 v[198:201], v[204:205], off offset:16
	v_pk_add_f32 v[136:137], v[144:145], v[136:137]
	v_pk_add_f32 v[134:135], v[142:143], v[134:135]
	s_nop 0
	v_pk_mov_b32 v[138:139], v[134:135], v[136:137] op_sel:[1,0]
	v_mov_b32_e32 v135, v137
	v_pk_add_f32 v[134:135], v[138:139], v[134:135]
	s_nop 0
	v_add_f32_e32 v0, v134, v135
	v_fmamk_f32 v0, v0, 0x3a800000, v211
	v_rsq_f32_e32 v0, v0
	s_nop 0
	v_pk_mul_f32 v[136:137], v[62:63], v[0:1] op_sel_hi:[1,0]
	v_pk_mul_f32 v[140:141], v[58:59], v[0:1] op_sel_hi:[1,0]
	v_mul_f32_e32 v142, 0xbfb8aa3b, v136
	v_exp_f32_e32 v142, v142
	v_mul_f32_e32 v143, 0xbfb8aa3b, v140
	v_exp_f32_e32 v143, v143
	v_pk_mul_f32 v[134:135], v[64:65], v[0:1] op_sel_hi:[1,0]
	v_add_f32_e32 v142, 1.0, v142
	v_rcp_f32_e32 v142, v142
	v_add_f32_e32 v143, 1.0, v143
	v_rcp_f32_e32 v143, v143
	v_pk_mul_f32 v[138:139], v[60:61], v[0:1] op_sel_hi:[1,0]
	v_mul_f32_e32 v136, v136, v142
	v_cndmask_b32_e32 v136, v142, v136, vcc
	v_mul_f32_e32 v140, v140, v143
	v_mul_f32_e32 v142, 0xbfb8aa3b, v137
	v_cndmask_b32_e32 v140, v143, v140, vcc
	v_exp_f32_e32 v142, v142
	v_mul_f32_e32 v143, 0xbfb8aa3b, v141
	v_exp_f32_e32 v143, v143
	v_add_f32_e32 v142, 1.0, v142
	v_rcp_f32_e32 v142, v142
	v_add_f32_e32 v143, 1.0, v143
	v_rcp_f32_e32 v143, v143
	v_mul_f32_e32 v137, v137, v142
	v_cndmask_b32_e32 v137, v142, v137, vcc
	v_mul_f32_e32 v141, v141, v143
	v_mul_f32_e32 v142, 0xbfb8aa3b, v134
	v_cndmask_b32_e32 v141, v143, v141, vcc
	v_exp_f32_e32 v142, v142
	v_mul_f32_e32 v143, 0xbfb8aa3b, v138
	v_exp_f32_e32 v143, v143
	v_add_f32_e32 v142, 1.0, v142
	v_rcp_f32_e32 v142, v142
	v_add_f32_e32 v143, 1.0, v143
	v_rcp_f32_e32 v143, v143
	v_mul_f32_e32 v134, v134, v142
	v_cndmask_b32_e32 v142, v142, v134, vcc
	v_mul_f32_e32 v134, v138, v143
	v_cndmask_b32_e32 v138, v143, v134, vcc
	v_mul_f32_e32 v134, 0xbfb8aa3b, v135
	v_exp_f32_e32 v134, v134
	v_mul_f32_e32 v143, 0xbfb8aa3b, v139
	v_exp_f32_e32 v143, v143
	v_add_f32_e32 v134, 1.0, v134
	v_rcp_f32_e32 v134, v134
	v_add_f32_e32 v143, 1.0, v143
	v_rcp_f32_e32 v143, v143
	v_mul_f32_e32 v135, v135, v134
	v_cndmask_b32_e32 v135, v134, v135, vcc
	v_mul_f32_e32 v134, v139, v143
	v_cndmask_b32_e32 v139, v143, v134, vcc
	v_cvt_pk_bf16_f32 v134, v136, v137
	v_cvt_pk_bf16_f32 v135, v142, v135
	v_cvt_pk_bf16_f32 v136, v140, v141
	v_cvt_pk_bf16_f32 v137, v138, v139
	global_store_dwordx4 v[132:133], v[134:137], off
	v_pk_mul_f32 v[138:139], v[48:49], v[0:1] op_sel_hi:[1,0]
	v_pk_mul_f32 v[140:141], v[46:47], v[0:1] op_sel_hi:[1,0]
	v_pk_mul_f32 v[136:137], v[54:55], v[0:1] op_sel_hi:[1,0]
	v_pk_mul_f32 v[134:135], v[56:57], v[0:1] op_sel_hi:[1,0]
	v_mul_f32_e32 v0, 0xbfb8aa3b, v136
	v_exp_f32_e32 v0, v0
	v_mul_f32_e32 v142, 0xbfb8aa3b, v140
	v_exp_f32_e32 v142, v142
	v_add_f32_e32 v0, 1.0, v0
	v_rcp_f32_e32 v0, v0
	v_add_f32_e32 v142, 1.0, v142
	v_rcp_f32_e32 v142, v142
	v_mul_f32_e32 v136, v136, v0
	v_cndmask_b32_e32 v0, v0, v136, vcc
	v_mul_f32_e32 v136, v140, v142
	v_mul_f32_e32 v140, 0xbfb8aa3b, v137
	v_cndmask_b32_e32 v136, v142, v136, vcc
	v_exp_f32_e32 v140, v140
	v_mul_f32_e32 v142, 0xbfb8aa3b, v141
	v_exp_f32_e32 v142, v142
	v_add_f32_e32 v140, 1.0, v140
	v_rcp_f32_e32 v140, v140
	v_add_f32_e32 v142, 1.0, v142
	v_rcp_f32_e32 v142, v142
	v_mul_f32_e32 v137, v137, v140
	v_cndmask_b32_e32 v137, v140, v137, vcc
	v_mul_f32_e32 v140, v141, v142
	v_mul_f32_e32 v141, 0xbfb8aa3b, v134
	v_cndmask_b32_e32 v140, v142, v140, vcc
	v_exp_f32_e32 v141, v141
	v_mul_f32_e32 v142, 0xbfb8aa3b, v138
	v_exp_f32_e32 v142, v142
	v_add_f32_e32 v141, 1.0, v141
	v_rcp_f32_e32 v141, v141
	v_add_f32_e32 v142, 1.0, v142
	v_rcp_f32_e32 v142, v142
	v_mul_f32_e32 v134, v134, v141
	v_cndmask_b32_e32 v141, v141, v134, vcc
	v_mul_f32_e32 v134, v138, v142
	v_cndmask_b32_e32 v138, v142, v134, vcc
	v_mul_f32_e32 v134, 0xbfb8aa3b, v135
	v_exp_f32_e32 v134, v134
	v_mul_f32_e32 v142, 0xbfb8aa3b, v139
	v_exp_f32_e32 v142, v142
	v_add_f32_e32 v134, 1.0, v134
	v_rcp_f32_e32 v134, v134
	v_add_f32_e32 v142, 1.0, v142
	v_rcp_f32_e32 v142, v142
	v_mul_f32_e32 v135, v135, v134
	v_cndmask_b32_e32 v135, v134, v135, vcc
	v_mul_f32_e32 v134, v139, v142
	v_cndmask_b32_e32 v139, v142, v134, vcc
	v_cvt_pk_bf16_f32 v134, v0, v137
	v_cvt_pk_bf16_f32 v135, v141, v135
	v_cvt_pk_bf16_f32 v136, v136, v140
	v_cvt_pk_bf16_f32 v137, v138, v139
	global_store_dwordx4 v[132:133], v[134:137], off offset:64
	s_nop 1
	v_add_u32_e32 v134, 0x90, v170
	v_ashrrev_i32_e32 v135, 31, v134
	v_lshlrev_b64 v[132:133], 11, v[134:135]
	v_lshl_add_u64 v[132:133], v[130:131], 0, v[132:133]
	s_waitcnt vmcnt(2)
	v_pk_add_f32 v[136:137], v[188:189], v[192:193]
	v_pk_add_f32 v[134:135], v[186:187], v[190:191]
	v_pk_add_f32 v[144:145], v[196:197], v[200:201]
	v_pk_add_f32 v[142:143], v[194:195], v[198:199]
	v_add_u32_e32 v202, 0xa0, v170
	v_ashrrev_i32_e32 v203, 31, v202
	v_lshlrev_b64 v[202:203], 6, v[202:203]
	v_lshl_add_u64 v[204:205], s[92:93], 0, v[202:203]
	global_load_dwordx4 v[186:189], v[204:205], off offset:32
	global_load_dwordx4 v[190:193], v[204:205], off offset:48
	global_load_dwordx4 v[194:197], v[204:205], off
	global_load_dwordx4 v[198:201], v[204:205], off offset:16
	v_pk_add_f32 v[136:137], v[144:145], v[136:137]
	v_pk_add_f32 v[134:135], v[142:143], v[134:135]
	s_nop 0
	v_pk_mov_b32 v[138:139], v[134:135], v[136:137] op_sel:[1,0]
	v_mov_b32_e32 v135, v137
	v_pk_add_f32 v[134:135], v[138:139], v[134:135]
	s_nop 0
	v_add_f32_e32 v0, v134, v135
	v_fmamk_f32 v0, v0, 0x3a800000, v211
	v_rsq_f32_e32 v0, v0
	s_nop 0
	v_pk_mul_f32 v[136:137], v[50:51], v[0:1] op_sel_hi:[1,0]
	v_pk_mul_f32 v[140:141], v[42:43], v[0:1] op_sel_hi:[1,0]
	v_mul_f32_e32 v142, 0xbfb8aa3b, v136
	v_exp_f32_e32 v142, v142
	v_mul_f32_e32 v143, 0xbfb8aa3b, v140
	v_exp_f32_e32 v143, v143
	v_pk_mul_f32 v[134:135], v[52:53], v[0:1] op_sel_hi:[1,0]
	v_add_f32_e32 v142, 1.0, v142
	v_rcp_f32_e32 v142, v142
	v_add_f32_e32 v143, 1.0, v143
	v_rcp_f32_e32 v143, v143
	v_pk_mul_f32 v[138:139], v[44:45], v[0:1] op_sel_hi:[1,0]
	v_mul_f32_e32 v136, v136, v142
	v_cndmask_b32_e32 v136, v142, v136, vcc
	v_mul_f32_e32 v140, v140, v143
	v_mul_f32_e32 v142, 0xbfb8aa3b, v137
	v_cndmask_b32_e32 v140, v143, v140, vcc
	v_exp_f32_e32 v142, v142
	v_mul_f32_e32 v143, 0xbfb8aa3b, v141
	v_exp_f32_e32 v143, v143
	v_add_f32_e32 v142, 1.0, v142
	v_rcp_f32_e32 v142, v142
	v_add_f32_e32 v143, 1.0, v143
	v_rcp_f32_e32 v143, v143
	v_mul_f32_e32 v137, v137, v142
	v_cndmask_b32_e32 v137, v142, v137, vcc
	v_mul_f32_e32 v141, v141, v143
	v_mul_f32_e32 v142, 0xbfb8aa3b, v134
	v_cndmask_b32_e32 v141, v143, v141, vcc
	v_exp_f32_e32 v142, v142
	v_mul_f32_e32 v143, 0xbfb8aa3b, v138
	v_exp_f32_e32 v143, v143
	v_add_f32_e32 v142, 1.0, v142
	v_rcp_f32_e32 v142, v142
	v_add_f32_e32 v143, 1.0, v143
	v_rcp_f32_e32 v143, v143
	v_mul_f32_e32 v134, v134, v142
	v_cndmask_b32_e32 v142, v142, v134, vcc
	v_mul_f32_e32 v134, v138, v143
	v_cndmask_b32_e32 v138, v143, v134, vcc
	v_mul_f32_e32 v134, 0xbfb8aa3b, v135
	v_exp_f32_e32 v134, v134
	v_mul_f32_e32 v143, 0xbfb8aa3b, v139
	v_exp_f32_e32 v143, v143
	v_add_f32_e32 v134, 1.0, v134
	v_rcp_f32_e32 v134, v134
	v_add_f32_e32 v143, 1.0, v143
	v_rcp_f32_e32 v143, v143
	v_mul_f32_e32 v135, v135, v134
	v_cndmask_b32_e32 v135, v134, v135, vcc
	v_mul_f32_e32 v134, v139, v143
	v_cndmask_b32_e32 v139, v143, v134, vcc
	v_cvt_pk_bf16_f32 v134, v136, v137
	v_cvt_pk_bf16_f32 v135, v142, v135
	v_cvt_pk_bf16_f32 v136, v140, v141
	v_cvt_pk_bf16_f32 v137, v138, v139
	global_store_dwordx4 v[132:133], v[134:137], off
	v_pk_mul_f32 v[138:139], v[32:33], v[0:1] op_sel_hi:[1,0]
	v_pk_mul_f32 v[140:141], v[30:31], v[0:1] op_sel_hi:[1,0]
	v_pk_mul_f32 v[136:137], v[38:39], v[0:1] op_sel_hi:[1,0]
	v_pk_mul_f32 v[134:135], v[40:41], v[0:1] op_sel_hi:[1,0]
	v_mul_f32_e32 v0, 0xbfb8aa3b, v136
	v_exp_f32_e32 v0, v0
	v_mul_f32_e32 v142, 0xbfb8aa3b, v140
	v_exp_f32_e32 v142, v142
	v_add_f32_e32 v0, 1.0, v0
	v_rcp_f32_e32 v0, v0
	v_add_f32_e32 v142, 1.0, v142
	v_rcp_f32_e32 v142, v142
	v_mul_f32_e32 v136, v136, v0
	v_cndmask_b32_e32 v0, v0, v136, vcc
	v_mul_f32_e32 v136, v140, v142
	v_mul_f32_e32 v140, 0xbfb8aa3b, v137
	v_cndmask_b32_e32 v136, v142, v136, vcc
	v_exp_f32_e32 v140, v140
	v_mul_f32_e32 v142, 0xbfb8aa3b, v141
	v_exp_f32_e32 v142, v142
	v_add_f32_e32 v140, 1.0, v140
	v_rcp_f32_e32 v140, v140
	v_add_f32_e32 v142, 1.0, v142
	v_rcp_f32_e32 v142, v142
	v_mul_f32_e32 v137, v137, v140
	v_cndmask_b32_e32 v137, v140, v137, vcc
	v_mul_f32_e32 v140, v141, v142
	v_mul_f32_e32 v141, 0xbfb8aa3b, v134
	v_cndmask_b32_e32 v140, v142, v140, vcc
	v_exp_f32_e32 v141, v141
	v_mul_f32_e32 v142, 0xbfb8aa3b, v138
	v_exp_f32_e32 v142, v142
	v_add_f32_e32 v141, 1.0, v141
	v_rcp_f32_e32 v141, v141
	v_add_f32_e32 v142, 1.0, v142
	v_rcp_f32_e32 v142, v142
	v_mul_f32_e32 v134, v134, v141
	v_cndmask_b32_e32 v141, v141, v134, vcc
	v_mul_f32_e32 v134, v138, v142
	v_cndmask_b32_e32 v138, v142, v134, vcc
	v_mul_f32_e32 v134, 0xbfb8aa3b, v135
	v_exp_f32_e32 v134, v134
	v_mul_f32_e32 v142, 0xbfb8aa3b, v139
	v_exp_f32_e32 v142, v142
	v_add_f32_e32 v134, 1.0, v134
	v_rcp_f32_e32 v134, v134
	v_add_f32_e32 v142, 1.0, v142
	v_rcp_f32_e32 v142, v142
	v_mul_f32_e32 v135, v135, v134
	v_cndmask_b32_e32 v135, v134, v135, vcc
	v_mul_f32_e32 v134, v139, v142
	v_cndmask_b32_e32 v139, v142, v134, vcc
	v_cvt_pk_bf16_f32 v134, v0, v137
	v_cvt_pk_bf16_f32 v135, v141, v135
	v_cvt_pk_bf16_f32 v136, v136, v140
	v_cvt_pk_bf16_f32 v137, v138, v139
	global_store_dwordx4 v[132:133], v[134:137], off offset:64
	s_nop 1
	v_add_u32_e32 v134, 0xa0, v170
	v_ashrrev_i32_e32 v135, 31, v134
	v_lshlrev_b64 v[132:133], 11, v[134:135]
	v_lshl_add_u64 v[132:133], v[130:131], 0, v[132:133]
	s_waitcnt vmcnt(2)
	v_pk_add_f32 v[136:137], v[188:189], v[192:193]
	v_pk_add_f32 v[134:135], v[186:187], v[190:191]
	v_pk_add_f32 v[144:145], v[196:197], v[200:201]
	v_pk_add_f32 v[142:143], v[194:195], v[198:199]
	v_pk_add_f32 v[136:137], v[144:145], v[136:137]
	v_pk_add_f32 v[134:135], v[142:143], v[134:135]
	s_nop 0
	v_pk_mov_b32 v[138:139], v[134:135], v[136:137] op_sel:[1,0]
	v_mov_b32_e32 v135, v137
	v_pk_add_f32 v[134:135], v[138:139], v[134:135]
	s_nop 0
	v_add_f32_e32 v0, v134, v135
	v_fmamk_f32 v0, v0, 0x3a800000, v211
	v_rsq_f32_e32 v0, v0
	s_nop 0
	v_pk_mul_f32 v[136:137], v[34:35], v[0:1] op_sel_hi:[1,0]
	v_pk_mul_f32 v[140:141], v[26:27], v[0:1] op_sel_hi:[1,0]
	v_mul_f32_e32 v142, 0xbfb8aa3b, v136
	v_exp_f32_e32 v142, v142
	v_mul_f32_e32 v143, 0xbfb8aa3b, v140
	v_exp_f32_e32 v143, v143
	v_pk_mul_f32 v[134:135], v[36:37], v[0:1] op_sel_hi:[1,0]
	v_add_f32_e32 v142, 1.0, v142
	v_rcp_f32_e32 v142, v142
	v_add_f32_e32 v143, 1.0, v143
	v_rcp_f32_e32 v143, v143
	v_pk_mul_f32 v[138:139], v[28:29], v[0:1] op_sel_hi:[1,0]
	v_mul_f32_e32 v136, v136, v142
	v_cndmask_b32_e32 v136, v142, v136, vcc
	v_mul_f32_e32 v140, v140, v143
	v_mul_f32_e32 v142, 0xbfb8aa3b, v137
	v_cndmask_b32_e32 v140, v143, v140, vcc
	v_exp_f32_e32 v142, v142
	v_mul_f32_e32 v143, 0xbfb8aa3b, v141
	v_exp_f32_e32 v143, v143
	v_add_f32_e32 v142, 1.0, v142
	v_rcp_f32_e32 v142, v142
	v_add_f32_e32 v143, 1.0, v143
	v_rcp_f32_e32 v143, v143
	v_mul_f32_e32 v137, v137, v142
	v_cndmask_b32_e32 v137, v142, v137, vcc
	v_mul_f32_e32 v141, v141, v143
	v_mul_f32_e32 v142, 0xbfb8aa3b, v134
	v_cndmask_b32_e32 v141, v143, v141, vcc
	v_exp_f32_e32 v142, v142
	v_mul_f32_e32 v143, 0xbfb8aa3b, v138
	v_exp_f32_e32 v143, v143
	v_add_f32_e32 v142, 1.0, v142
	v_rcp_f32_e32 v142, v142
	v_add_f32_e32 v143, 1.0, v143
	v_rcp_f32_e32 v143, v143
	v_mul_f32_e32 v134, v134, v142
	v_cndmask_b32_e32 v142, v142, v134, vcc
	v_mul_f32_e32 v134, v138, v143
	v_cndmask_b32_e32 v138, v143, v134, vcc
	v_mul_f32_e32 v134, 0xbfb8aa3b, v135
	v_exp_f32_e32 v134, v134
	v_mul_f32_e32 v143, 0xbfb8aa3b, v139
	v_exp_f32_e32 v143, v143
	v_add_f32_e32 v134, 1.0, v134
	v_rcp_f32_e32 v134, v134
	v_add_f32_e32 v143, 1.0, v143
	v_rcp_f32_e32 v143, v143
	v_mul_f32_e32 v135, v135, v134
	v_cndmask_b32_e32 v135, v134, v135, vcc
	v_mul_f32_e32 v134, v139, v143
	v_cndmask_b32_e32 v139, v143, v134, vcc
	v_cvt_pk_bf16_f32 v134, v136, v137
	v_cvt_pk_bf16_f32 v135, v142, v135
	v_cvt_pk_bf16_f32 v136, v140, v141
	v_cvt_pk_bf16_f32 v137, v138, v139
	global_store_dwordx4 v[132:133], v[134:137], off
	v_pk_mul_f32 v[138:139], v[16:17], v[0:1] op_sel_hi:[1,0]
	v_pk_mul_f32 v[140:141], v[14:15], v[0:1] op_sel_hi:[1,0]
	v_pk_mul_f32 v[136:137], v[22:23], v[0:1] op_sel_hi:[1,0]
	v_pk_mul_f32 v[134:135], v[24:25], v[0:1] op_sel_hi:[1,0]
	v_mul_f32_e32 v0, 0xbfb8aa3b, v136
	v_exp_f32_e32 v0, v0
	v_mul_f32_e32 v142, 0xbfb8aa3b, v140
	v_exp_f32_e32 v142, v142
	v_add_f32_e32 v0, 1.0, v0
	v_rcp_f32_e32 v0, v0
	v_add_f32_e32 v142, 1.0, v142
	v_rcp_f32_e32 v142, v142
	v_mul_f32_e32 v136, v136, v0
	v_cndmask_b32_e32 v0, v0, v136, vcc
	v_mul_f32_e32 v136, v140, v142
	v_mul_f32_e32 v140, 0xbfb8aa3b, v137
	v_cndmask_b32_e32 v136, v142, v136, vcc
	v_exp_f32_e32 v140, v140
	v_mul_f32_e32 v142, 0xbfb8aa3b, v141
	v_exp_f32_e32 v142, v142
	v_add_f32_e32 v140, 1.0, v140
	v_rcp_f32_e32 v140, v140
	v_add_f32_e32 v142, 1.0, v142
	v_rcp_f32_e32 v142, v142
	v_mul_f32_e32 v137, v137, v140
	v_cndmask_b32_e32 v137, v140, v137, vcc
	v_mul_f32_e32 v140, v141, v142
	v_mul_f32_e32 v141, 0xbfb8aa3b, v134
	v_cndmask_b32_e32 v140, v142, v140, vcc
	v_exp_f32_e32 v141, v141
	v_mul_f32_e32 v142, 0xbfb8aa3b, v138
	v_exp_f32_e32 v142, v142
	v_add_f32_e32 v141, 1.0, v141
	v_rcp_f32_e32 v141, v141
	v_add_f32_e32 v142, 1.0, v142
	v_rcp_f32_e32 v142, v142
	v_mul_f32_e32 v134, v134, v141
	v_cndmask_b32_e32 v141, v141, v134, vcc
	v_mul_f32_e32 v134, v138, v142
	v_cndmask_b32_e32 v138, v142, v134, vcc
	v_mul_f32_e32 v134, 0xbfb8aa3b, v135
	v_exp_f32_e32 v134, v134
	v_mul_f32_e32 v142, 0xbfb8aa3b, v139
	v_exp_f32_e32 v142, v142
	v_add_f32_e32 v134, 1.0, v134
	v_rcp_f32_e32 v134, v134
	v_add_f32_e32 v142, 1.0, v142
	v_rcp_f32_e32 v142, v142
	v_mul_f32_e32 v135, v135, v134
	v_cndmask_b32_e32 v135, v134, v135, vcc
	v_mul_f32_e32 v134, v139, v142
	v_cndmask_b32_e32 v139, v142, v134, vcc
	v_cvt_pk_bf16_f32 v134, v0, v137
	v_cvt_pk_bf16_f32 v135, v141, v135
	v_cvt_pk_bf16_f32 v136, v136, v140
	v_cvt_pk_bf16_f32 v137, v138, v139
	global_store_dwordx4 v[132:133], v[134:137], off offset:64
	v_add_u32_e32 v132, 0xb0, v170
	v_ashrrev_i32_e32 v133, 31, v132
	v_lshlrev_b64 v[134:135], 11, v[132:133]
	v_lshlrev_b64 v[132:133], 6, v[132:133]
	v_lshl_add_u64 v[144:145], s[92:93], 0, v[132:133]
	v_lshl_add_u64 v[130:131], v[130:131], 0, v[134:135]
	global_load_dwordx4 v[132:135], v[144:145], off offset:32
	global_load_dwordx4 v[136:139], v[144:145], off offset:48
	global_load_dwordx4 v[140:143], v[144:145], off
	s_nop 0
	global_load_dwordx4 v[144:147], v[144:145], off offset:16
	s_waitcnt vmcnt(2)
	v_pk_add_f32 v[134:135], v[134:135], v[138:139]
	v_pk_add_f32 v[132:133], v[132:133], v[136:137]
	s_waitcnt vmcnt(0)
	v_pk_add_f32 v[142:143], v[142:143], v[146:147]
	v_pk_add_f32 v[140:141], v[140:141], v[144:145]
	v_pk_add_f32 v[134:135], v[142:143], v[134:135]
	v_pk_add_f32 v[132:133], v[140:141], v[132:133]
	s_nop 0
	v_pk_mov_b32 v[136:137], v[132:133], v[134:135] op_sel:[1,0]
	v_mov_b32_e32 v133, v135
	v_pk_add_f32 v[132:133], v[136:137], v[132:133]
	s_nop 0
	v_add_f32_e32 v0, v132, v133
	v_fmamk_f32 v0, v0, 0x3a800000, v211
	v_rsq_f32_e32 v0, v0
	s_nop 0
	v_pk_mul_f32 v[134:135], v[18:19], v[0:1] op_sel_hi:[1,0]
	v_pk_mul_f32 v[138:139], v[10:11], v[0:1] op_sel_hi:[1,0]
	v_mul_f32_e32 v140, 0xbfb8aa3b, v134
	v_exp_f32_e32 v140, v140
	v_mul_f32_e32 v141, 0xbfb8aa3b, v138
	v_exp_f32_e32 v141, v141
	v_pk_mul_f32 v[132:133], v[20:21], v[0:1] op_sel_hi:[1,0]
	v_add_f32_e32 v140, 1.0, v140
	v_rcp_f32_e32 v140, v140
	v_add_f32_e32 v141, 1.0, v141
	v_rcp_f32_e32 v141, v141
	v_pk_mul_f32 v[136:137], v[12:13], v[0:1] op_sel_hi:[1,0]
	v_mul_f32_e32 v134, v134, v140
	v_cndmask_b32_e32 v134, v140, v134, vcc
	v_mul_f32_e32 v138, v138, v141
	v_mul_f32_e32 v140, 0xbfb8aa3b, v135
	v_cndmask_b32_e32 v138, v141, v138, vcc
	v_exp_f32_e32 v140, v140
	v_mul_f32_e32 v141, 0xbfb8aa3b, v139
	v_exp_f32_e32 v141, v141
	v_add_f32_e32 v140, 1.0, v140
	v_rcp_f32_e32 v140, v140
	v_add_f32_e32 v141, 1.0, v141
	v_rcp_f32_e32 v141, v141
	v_mul_f32_e32 v135, v135, v140
	v_cndmask_b32_e32 v135, v140, v135, vcc
	v_mul_f32_e32 v139, v139, v141
	v_mul_f32_e32 v140, 0xbfb8aa3b, v132
	v_cndmask_b32_e32 v139, v141, v139, vcc
	v_exp_f32_e32 v140, v140
	v_mul_f32_e32 v141, 0xbfb8aa3b, v136
	v_exp_f32_e32 v141, v141
	v_add_f32_e32 v140, 1.0, v140
	v_rcp_f32_e32 v140, v140
	v_add_f32_e32 v141, 1.0, v141
	v_rcp_f32_e32 v141, v141
	v_mul_f32_e32 v132, v132, v140
	v_cndmask_b32_e32 v140, v140, v132, vcc
	v_mul_f32_e32 v132, v136, v141
	v_cndmask_b32_e32 v136, v141, v132, vcc
	v_mul_f32_e32 v132, 0xbfb8aa3b, v133
	v_exp_f32_e32 v132, v132
	v_mul_f32_e32 v141, 0xbfb8aa3b, v137
	v_exp_f32_e32 v141, v141
	v_add_f32_e32 v132, 1.0, v132
	v_rcp_f32_e32 v132, v132
	v_add_f32_e32 v141, 1.0, v141
	v_rcp_f32_e32 v141, v141
	v_mul_f32_e32 v133, v133, v132
	v_cndmask_b32_e32 v133, v132, v133, vcc
	v_mul_f32_e32 v132, v137, v141
	v_cndmask_b32_e32 v137, v141, v132, vcc
	v_cvt_pk_bf16_f32 v132, v134, v135
	v_cvt_pk_bf16_f32 v133, v140, v133
	v_cvt_pk_bf16_f32 v134, v138, v139
	v_cvt_pk_bf16_f32 v135, v136, v137
	global_store_dwordx4 v[130:131], v[132:135], off
	v_pk_mul_f32 v[136:137], v[4:5], v[0:1] op_sel_hi:[1,0]
	v_pk_mul_f32 v[138:139], v[2:3], v[0:1] op_sel_hi:[1,0]
	v_pk_mul_f32 v[134:135], v[6:7], v[0:1] op_sel_hi:[1,0]
	v_pk_mul_f32 v[132:133], v[8:9], v[0:1] op_sel_hi:[1,0]
	v_mul_f32_e32 v0, 0xbfb8aa3b, v134
	v_exp_f32_e32 v0, v0
	v_mul_f32_e32 v140, 0xbfb8aa3b, v138
	v_exp_f32_e32 v140, v140
	v_add_f32_e32 v0, 1.0, v0
	v_rcp_f32_e32 v0, v0
	v_add_f32_e32 v140, 1.0, v140
	v_rcp_f32_e32 v140, v140
	v_mul_f32_e32 v134, v134, v0
	v_cndmask_b32_e32 v0, v0, v134, vcc
	v_mul_f32_e32 v134, v138, v140
	v_mul_f32_e32 v138, 0xbfb8aa3b, v135
	v_cndmask_b32_e32 v134, v140, v134, vcc
	v_exp_f32_e32 v138, v138
	v_mul_f32_e32 v140, 0xbfb8aa3b, v139
	v_exp_f32_e32 v140, v140
	v_add_f32_e32 v138, 1.0, v138
	v_rcp_f32_e32 v138, v138
	v_add_f32_e32 v140, 1.0, v140
	v_rcp_f32_e32 v140, v140
	v_mul_f32_e32 v135, v135, v138
	v_cndmask_b32_e32 v135, v138, v135, vcc
	v_mul_f32_e32 v138, v139, v140
	v_mul_f32_e32 v139, 0xbfb8aa3b, v132
	v_cndmask_b32_e32 v138, v140, v138, vcc
	v_exp_f32_e32 v139, v139
	v_mul_f32_e32 v140, 0xbfb8aa3b, v136
	v_exp_f32_e32 v140, v140
	v_add_f32_e32 v139, 1.0, v139
	v_rcp_f32_e32 v139, v139
	v_add_f32_e32 v140, 1.0, v140
	v_rcp_f32_e32 v140, v140
	v_mul_f32_e32 v132, v132, v139
	v_cndmask_b32_e32 v139, v139, v132, vcc
	v_mul_f32_e32 v132, v136, v140
	v_cndmask_b32_e32 v136, v140, v132, vcc
	v_mul_f32_e32 v132, 0xbfb8aa3b, v133
	v_exp_f32_e32 v132, v132
	v_mul_f32_e32 v140, 0xbfb8aa3b, v137
	v_exp_f32_e32 v140, v140
	v_add_f32_e32 v132, 1.0, v132
	v_rcp_f32_e32 v132, v132
	v_add_f32_e32 v140, 1.0, v140
	v_rcp_f32_e32 v140, v140
	v_mul_f32_e32 v133, v133, v132
	v_cndmask_b32_e32 v133, v132, v133, vcc
	v_mul_f32_e32 v132, v137, v140
	v_cndmask_b32_e32 v137, v140, v132, vcc
	v_cvt_pk_bf16_f32 v132, v0, v135
	v_cvt_pk_bf16_f32 v133, v139, v133
	v_cvt_pk_bf16_f32 v134, v134, v138
	v_cvt_pk_bf16_f32 v135, v136, v137
	global_store_dwordx4 v[130:131], v[132:135], off offset:64

.LBB0_196:
	s_andn2_b64 vcc, exec, s[42:43]
	s_cbranch_vccnz .LBB0_198
	s_cmp_lt_i32 s16, 4
	s_cselect_b64 vcc, -1, 0
	s_and_b64 s[42:43], vcc, exec
	s_mov_b64 s[8:9], s[40:41]
	v_readlane_b32 s40, v253, 4
	v_readlane_b32 s41, v253, 5
	v_readlane_b32 s42, v253, 6
	v_readlane_b32 s50, v253, 14
	v_readlane_b32 s52, v253, 16
	v_readlane_b32 s46, v253, 10
	v_readlane_b32 s51, v253, 15
	v_readlane_b32 s53, v253, 17
	s_mov_b64 s[40:41], s[8:9]
	s_cselect_b32 s22, s50, s52
	s_mov_b32 s42, 0xcc00000
	v_readlane_b32 s8, v255, 43
	v_readlane_b32 s43, v253, 7
	s_cselect_b32 s17, s51, s53
	s_cselect_b32 s46, s42, 0xec00000
	v_readlane_b32 s9, v255, 44
	s_add_u32 s42, s22, s8
	s_addc_u32 s43, s17, s9
	global_load_dwordx4 v[130:133], v225, s[42:43] offset:16
	global_load_dwordx4 v[134:137], v225, s[42:43]
	v_cndmask_b32_e32 v0, 1.0, v216, vcc
	v_ashrrev_i32_e32 v171, 31, v170
	s_lshl_b32 s17, s16, 8
	v_readlane_b32 s54, v253, 18
	v_readlane_b32 s55, v253, 19
	s_mov_b32 s55, s91
	s_movk_i32 s54, 0x100
	v_readlane_b32 s44, v253, 8
	v_readlane_b32 s45, v253, 9
	v_readlane_b32 s47, v253, 11
	v_readlane_b32 s48, v253, 12
	v_readlane_b32 s49, v253, 13
	s_waitcnt vmcnt(0)
	v_pk_mul_f32 v[138:139], v[0:1], v[132:133] op_sel_hi:[0,1]
	v_pk_mul_f32 v[140:141], v[0:1], v[130:131] op_sel_hi:[0,1]
	global_load_dwordx4 v[146:149], v225, s[42:43] offset:144
	global_load_dwordx4 v[130:133], v225, s[42:43] offset:128
	v_pk_mul_f32 v[142:143], v[0:1], v[136:137] op_sel_hi:[0,1]
	v_pk_mul_f32 v[144:145], v[0:1], v[134:135] op_sel_hi:[0,1]
	s_add_u32 s42, s38, s46
	s_addc_u32 s43, s39, 0
	s_and_b32 s17, s17, 0x300
	s_waitcnt vmcnt(0)
	v_pk_mul_f32 v[136:137], v[0:1], v[130:131] op_sel_hi:[0,1]
	v_pk_mul_f32 v[130:131], v[0:1], v[148:149] op_sel_hi:[0,1]
	v_lshlrev_b64 v[148:149], 6, v[170:171]
	v_lshl_add_u64 v[148:149], s[92:93], 0, v[148:149]
	global_load_dwordx4 v[152:155], v[148:149], off offset:32
	global_load_dwordx4 v[172:175], v[148:149], off offset:48
	global_load_dwordx4 v[186:189], v[148:149], off
	global_load_dwordx4 v[190:193], v[148:149], off offset:16
	v_pk_mul_f32 v[134:135], v[0:1], v[132:133] op_sel_hi:[0,1]
	v_pk_mul_f32 v[132:133], v[0:1], v[146:147] op_sel_hi:[0,1]
	v_and_b32_e32 v147, 64, v217
	v_xor_b32_e32 v146, 16, v217
	v_add_u32_e32 v147, 64, v147
	v_cmp_lt_i32_e32 vcc, v146, v147
	v_or_b32_e32 v0, s17, v222
	v_lshlrev_b32_e32 v0, 1, v0
	v_cndmask_b32_e32 v146, v217, v146, vcc
	v_lshlrev_b32_e32 v150, 2, v146
	v_xor_b32_e32 v146, 32, v217
	v_cmp_lt_i32_e32 vcc, v146, v147
	s_waitcnt vmcnt(2)
	v_pk_add_f32 v[154:155], v[154:155], v[174:175]
	v_pk_add_f32 v[152:153], v[152:153], v[172:173]
	s_waitcnt vmcnt(0)
	v_pk_add_f32 v[148:149], v[188:189], v[192:193]
	v_pk_add_f32 v[156:157], v[186:187], v[190:191]
	v_or_b32_e32 v226, 16, v170
	v_ashrrev_i32_e32 v227, 31, v226
	v_lshlrev_b64 v[226:227], 6, v[226:227]
	v_lshl_add_u64 v[228:229], s[92:93], 0, v[226:227]
	global_load_dwordx4 v[194:197], v[228:229], off offset:32
	global_load_dwordx4 v[198:201], v[228:229], off offset:48
	global_load_dwordx4 v[202:205], v[228:229], off
	global_load_dwordx4 v[206:209], v[228:229], off offset:16
	v_pk_add_f32 v[148:149], v[148:149], v[154:155]
	v_pk_add_f32 v[152:153], v[156:157], v[152:153]
	v_cndmask_b32_e32 v146, v217, v146, vcc
	v_pk_mov_b32 v[154:155], v[152:153], v[148:149] op_sel:[1,0]
	v_mov_b32_e32 v153, v149
	v_pk_add_f32 v[148:149], v[154:155], v[152:153]
	v_lshlrev_b32_e32 v151, 2, v146
	v_lshl_add_u64 v[146:147], s[42:43], 0, v[0:1]
	v_add_f32_e32 v0, v148, v149
	v_pk_mul_f32 v[148:149], v[128:129], v[128:129]
	v_pk_mul_f32 v[152:153], v[126:127], v[126:127]
	v_pk_mul_f32 v[172:173], v[112:113], v[112:113]
	v_pk_mov_b32 v[154:155], v[152:153], v[148:149] op_sel:[1,0]
	v_mov_b32_e32 v153, v149
	v_pk_add_f32 v[148:149], v[154:155], v[152:153]
	v_pk_mul_f32 v[152:153], v[124:125], v[124:125]
	v_pk_mul_f32 v[154:155], v[122:123], v[122:123]
	v_pk_add_f32 v[148:149], v[148:149], v[148:149] op_sel:[0,1] op_sel_hi:[1,0]
	v_pk_mov_b32 v[156:157], v[154:155], v[152:153] op_sel:[1,0]
	v_mov_b32_e32 v155, v153
	v_pk_add_f32 v[152:153], v[156:157], v[154:155]
	v_pk_mul_f32 v[154:155], v[120:121], v[120:121]
	v_pk_add_f32 v[152:153], v[152:153], v[152:153] op_sel:[0,1] op_sel_hi:[1,0]
	v_pk_mul_f32 v[156:157], v[118:119], v[118:119]
	v_pk_mul_f32 v[174:175], v[110:111], v[110:111]
	v_add_f32_e32 v156, v156, v157
	v_add_f32_e32 v154, v154, v155
	v_mov_b32_e32 v149, v174
	v_mov_b32_e32 v153, v175
	v_mov_b32_e32 v157, v172
	v_mov_b32_e32 v155, v173
	v_pk_add_f32 v[148:149], v[148:149], v[152:153]
	v_pk_add_f32 v[152:153], v[156:157], v[154:155]
	v_fmamk_f32 v0, v0, 0x3a800000, v211
	v_pk_add_f32 v[148:149], v[148:149], v[152:153]
	v_rsq_f32_e32 v0, v0
	v_add_f32_e32 v148, v148, v149
	ds_bpermute_b32 v149, v150, v148
	s_waitcnt lgkmcnt(0)
	v_add_f32_e32 v148, v148, v149
	ds_bpermute_b32 v149, v151, v148
	s_waitcnt lgkmcnt(0)
	v_add_f32_e32 v148, v148, v149
	v_mul_f32_e32 v148, v148, v0
	v_mul_f32_e32 v148, v0, v148
	v_fmamk_f32 v148, v148, 0x3c800000, v211
	v_rsq_f32_e32 v148, v148
	s_nop 0
	v_mul_f32_e32 v0, v0, v148
	v_pk_mul_f32 v[152:153], v[126:127], v[0:1] op_sel_hi:[1,0]
	v_pk_mul_f32 v[154:155], v[128:129], v[0:1] op_sel_hi:[1,0]
	v_lshlrev_b64 v[148:149], 11, v[170:171]
	v_pk_mul_f32 v[154:155], v[142:143], v[154:155]
	v_pk_mul_f32 v[152:153], v[144:145], v[152:153]
	v_pk_mul_f32 v[156:157], v[122:123], v[0:1] op_sel_hi:[1,0]
	v_pk_mul_f32 v[172:173], v[124:125], v[0:1] op_sel_hi:[1,0]
	v_lshl_add_u64 v[148:149], v[146:147], 0, v[148:149]
	v_pk_mul_f32 v[172:173], v[138:139], v[172:173]
	v_pk_mul_f32 v[156:157], v[140:141], v[156:157]
	v_cvt_pk_bf16_f32 v152, v152, v153
	v_cvt_pk_bf16_f32 v153, v154, v155
	s_nop 0
	v_cvt_pk_bf16_f32 v154, v156, v157
	v_cvt_pk_bf16_f32 v155, v172, v173
	global_store_dwordx4 v[148:149], v[152:155], off
	v_pk_mul_f32 v[156:157], v[110:111], v[0:1] op_sel_hi:[1,0]
	v_pk_mul_f32 v[172:173], v[112:113], v[0:1] op_sel_hi:[1,0]
	v_pk_mul_f32 v[152:153], v[118:119], v[0:1] op_sel_hi:[1,0]
	v_pk_mul_f32 v[154:155], v[120:121], v[0:1] op_sel_hi:[1,0]
	v_pk_mul_f32 v[152:153], v[136:137], v[152:153]
	v_pk_mul_f32 v[154:155], v[134:135], v[154:155]
	v_pk_mul_f32 v[172:173], v[130:131], v[172:173]
	v_pk_mul_f32 v[156:157], v[132:133], v[156:157]
	v_cvt_pk_bf16_f32 v152, v152, v153
	v_cvt_pk_bf16_f32 v153, v154, v155
	s_nop 0
	v_cvt_pk_bf16_f32 v154, v156, v157
	v_cvt_pk_bf16_f32 v155, v172, v173
	global_store_dwordx4 v[148:149], v[152:155], off offset:64
	v_or_b32_e32 v148, 16, v170
	v_ashrrev_i32_e32 v149, 31, v148
	v_lshlrev_b64 v[148:149], 11, v[148:149]
	v_lshl_add_u64 v[148:149], v[146:147], 0, v[148:149]
	s_waitcnt vmcnt(2)
	v_pk_add_f32 v[154:155], v[196:197], v[200:201]
	v_pk_add_f32 v[152:153], v[194:195], v[198:199]
	v_pk_add_f32 v[156:157], v[204:205], v[208:209]
	v_pk_add_f32 v[176:177], v[202:203], v[206:207]
	v_or_b32_e32 v226, 32, v170
	v_ashrrev_i32_e32 v227, 31, v226
	v_lshlrev_b64 v[226:227], 6, v[226:227]
	v_lshl_add_u64 v[228:229], s[92:93], 0, v[226:227]
	global_load_dwordx4 v[194:197], v[228:229], off offset:32
	global_load_dwordx4 v[198:201], v[228:229], off offset:48
	global_load_dwordx4 v[202:205], v[228:229], off
	global_load_dwordx4 v[206:209], v[228:229], off offset:16
	v_pk_add_f32 v[154:155], v[156:157], v[154:155]
	v_pk_add_f32 v[152:153], v[176:177], v[152:153]
	v_pk_mul_f32 v[174:175], v[96:97], v[96:97]
	v_pk_mov_b32 v[156:157], v[152:153], v[154:155] op_sel:[1,0]
	v_mov_b32_e32 v153, v155
	v_pk_add_f32 v[152:153], v[156:157], v[152:153]
	v_pk_mul_f32 v[154:155], v[114:115], v[114:115]
	v_add_f32_e32 v0, v152, v153
	v_pk_mul_f32 v[152:153], v[116:117], v[116:117]
	v_pk_mul_f32 v[176:177], v[94:95], v[94:95]
	v_pk_mov_b32 v[156:157], v[154:155], v[152:153] op_sel:[1,0]
	v_mov_b32_e32 v155, v153
	v_pk_add_f32 v[152:153], v[156:157], v[154:155]
	v_pk_mul_f32 v[154:155], v[108:109], v[108:109]
	v_pk_mul_f32 v[156:157], v[106:107], v[106:107]
	v_pk_add_f32 v[152:153], v[152:153], v[152:153] op_sel:[0,1] op_sel_hi:[1,0]
	v_pk_mov_b32 v[172:173], v[156:157], v[154:155] op_sel:[1,0]
	v_mov_b32_e32 v157, v155
	v_pk_add_f32 v[154:155], v[172:173], v[156:157]
	v_pk_mul_f32 v[156:157], v[104:105], v[104:105]
	v_pk_add_f32 v[154:155], v[154:155], v[154:155] op_sel:[0,1] op_sel_hi:[1,0]
	v_pk_mul_f32 v[172:173], v[102:103], v[102:103]
	v_add_f32_e32 v156, v156, v157
	v_add_f32_e32 v172, v172, v173
	v_mov_b32_e32 v153, v176
	v_mov_b32_e32 v155, v177
	v_mov_b32_e32 v173, v174
	v_mov_b32_e32 v157, v175
	v_pk_add_f32 v[152:153], v[152:153], v[154:155]
	v_pk_add_f32 v[154:155], v[172:173], v[156:157]
	v_fmamk_f32 v0, v0, 0x3a800000, v211
	v_pk_add_f32 v[152:153], v[152:153], v[154:155]
	v_rsq_f32_e32 v0, v0
	v_add_f32_e32 v152, v152, v153
	ds_bpermute_b32 v153, v150, v152
	s_waitcnt lgkmcnt(0)
	v_add_f32_e32 v152, v152, v153
	ds_bpermute_b32 v153, v151, v152
	s_waitcnt lgkmcnt(0)
	v_add_f32_e32 v152, v152, v153
	v_mul_f32_e32 v152, v152, v0
	v_mul_f32_e32 v152, v0, v152
	v_fmamk_f32 v152, v152, 0x3c800000, v211
	v_rsq_f32_e32 v152, v152
	s_nop 0
	v_mul_f32_e32 v0, v0, v152
	v_pk_mul_f32 v[152:153], v[114:115], v[0:1] op_sel_hi:[1,0]
	v_pk_mul_f32 v[154:155], v[116:117], v[0:1] op_sel_hi:[1,0]
	v_pk_mul_f32 v[152:153], v[144:145], v[152:153]
	v_pk_mul_f32 v[154:155], v[142:143], v[154:155]
	v_pk_mul_f32 v[156:157], v[106:107], v[0:1] op_sel_hi:[1,0]
	v_pk_mul_f32 v[172:173], v[108:109], v[0:1] op_sel_hi:[1,0]
	v_pk_mul_f32 v[156:157], v[140:141], v[156:157]
	v_pk_mul_f32 v[172:173], v[138:139], v[172:173]
	v_cvt_pk_bf16_f32 v152, v152, v153
	v_cvt_pk_bf16_f32 v153, v154, v155
	v_cvt_pk_bf16_f32 v154, v156, v157
	v_pk_mul_f32 v[156:157], v[94:95], v[0:1] op_sel_hi:[1,0]
	v_cvt_pk_bf16_f32 v155, v172, v173
	global_store_dwordx4 v[148:149], v[152:155], off
	v_pk_mul_f32 v[172:173], v[96:97], v[0:1] op_sel_hi:[1,0]
	v_pk_mul_f32 v[156:157], v[132:133], v[156:157]
	v_pk_mul_f32 v[152:153], v[102:103], v[0:1] op_sel_hi:[1,0]
	v_pk_mul_f32 v[154:155], v[104:105], v[0:1] op_sel_hi:[1,0]
	v_pk_mul_f32 v[152:153], v[136:137], v[152:153]
	v_pk_mul_f32 v[154:155], v[134:135], v[154:155]
	v_pk_mul_f32 v[172:173], v[130:131], v[172:173]
	v_cvt_pk_bf16_f32 v152, v152, v153
	v_cvt_pk_bf16_f32 v153, v154, v155
	v_cvt_pk_bf16_f32 v154, v156, v157
	s_nop 0
	v_cvt_pk_bf16_f32 v155, v172, v173
	global_store_dwordx4 v[148:149], v[152:155], off offset:64
	v_or_b32_e32 v148, 32, v170
	v_ashrrev_i32_e32 v149, 31, v148
	v_lshlrev_b64 v[148:149], 11, v[148:149]
	v_lshl_add_u64 v[148:149], v[146:147], 0, v[148:149]
	s_waitcnt vmcnt(2)
	v_pk_add_f32 v[154:155], v[196:197], v[200:201]
	v_pk_add_f32 v[152:153], v[194:195], v[198:199]
	v_pk_add_f32 v[156:157], v[204:205], v[208:209]
	v_pk_add_f32 v[176:177], v[202:203], v[206:207]
	v_or_b32_e32 v226, 48, v170
	v_ashrrev_i32_e32 v227, 31, v226
	v_lshlrev_b64 v[226:227], 6, v[226:227]
	v_lshl_add_u64 v[228:229], s[92:93], 0, v[226:227]
	global_load_dwordx4 v[194:197], v[228:229], off offset:32
	global_load_dwordx4 v[198:201], v[228:229], off offset:48
	global_load_dwordx4 v[202:205], v[228:229], off
	global_load_dwordx4 v[206:209], v[228:229], off offset:16
	v_pk_add_f32 v[154:155], v[156:157], v[154:155]
	v_pk_add_f32 v[152:153], v[176:177], v[152:153]
	v_pk_mul_f32 v[174:175], v[80:81], v[80:81]
	v_pk_mov_b32 v[156:157], v[152:153], v[154:155] op_sel:[1,0]
	v_mov_b32_e32 v153, v155
	v_pk_add_f32 v[152:153], v[156:157], v[152:153]
	v_pk_mul_f32 v[154:155], v[98:99], v[98:99]
	v_add_f32_e32 v0, v152, v153
	v_pk_mul_f32 v[152:153], v[100:101], v[100:101]
	v_pk_mul_f32 v[176:177], v[78:79], v[78:79]
	v_pk_mov_b32 v[156:157], v[154:155], v[152:153] op_sel:[1,0]
	v_mov_b32_e32 v155, v153
	v_pk_add_f32 v[152:153], v[156:157], v[154:155]
	v_pk_mul_f32 v[154:155], v[92:93], v[92:93]
	v_pk_mul_f32 v[156:157], v[90:91], v[90:91]
	v_pk_add_f32 v[152:153], v[152:153], v[152:153] op_sel:[0,1] op_sel_hi:[1,0]
	v_pk_mov_b32 v[172:173], v[156:157], v[154:155] op_sel:[1,0]
	v_mov_b32_e32 v157, v155
	v_pk_add_f32 v[154:155], v[172:173], v[156:157]
	v_pk_mul_f32 v[156:157], v[88:89], v[88:89]
	v_pk_add_f32 v[154:155], v[154:155], v[154:155] op_sel:[0,1] op_sel_hi:[1,0]
	v_pk_mul_f32 v[172:173], v[86:87], v[86:87]
	v_add_f32_e32 v156, v156, v157
	v_add_f32_e32 v172, v172, v173
	v_mov_b32_e32 v153, v176
	v_mov_b32_e32 v155, v177
	v_mov_b32_e32 v173, v174
	v_mov_b32_e32 v157, v175
	v_pk_add_f32 v[152:153], v[152:153], v[154:155]
	v_pk_add_f32 v[154:155], v[172:173], v[156:157]
	v_fmamk_f32 v0, v0, 0x3a800000, v211
	v_pk_add_f32 v[152:153], v[152:153], v[154:155]
	v_rsq_f32_e32 v0, v0
	v_add_f32_e32 v152, v152, v153
	ds_bpermute_b32 v153, v150, v152
	s_waitcnt lgkmcnt(0)
	v_add_f32_e32 v152, v152, v153
	ds_bpermute_b32 v153, v151, v152
	s_waitcnt lgkmcnt(0)
	v_add_f32_e32 v152, v152, v153
	v_mul_f32_e32 v152, v152, v0
	v_mul_f32_e32 v152, v0, v152
	v_fmamk_f32 v152, v152, 0x3c800000, v211
	v_rsq_f32_e32 v152, v152
	s_nop 0
	v_mul_f32_e32 v0, v0, v152
	v_pk_mul_f32 v[152:153], v[98:99], v[0:1] op_sel_hi:[1,0]
	v_pk_mul_f32 v[154:155], v[100:101], v[0:1] op_sel_hi:[1,0]
	v_pk_mul_f32 v[152:153], v[144:145], v[152:153]
	v_pk_mul_f32 v[154:155], v[142:143], v[154:155]
	v_pk_mul_f32 v[156:157], v[90:91], v[0:1] op_sel_hi:[1,0]
	v_pk_mul_f32 v[172:173], v[92:93], v[0:1] op_sel_hi:[1,0]
	v_pk_mul_f32 v[156:157], v[140:141], v[156:157]
	v_pk_mul_f32 v[172:173], v[138:139], v[172:173]
	v_cvt_pk_bf16_f32 v152, v152, v153
	v_cvt_pk_bf16_f32 v153, v154, v155
	v_cvt_pk_bf16_f32 v154, v156, v157
	v_pk_mul_f32 v[156:157], v[78:79], v[0:1] op_sel_hi:[1,0]
	v_cvt_pk_bf16_f32 v155, v172, v173
	global_store_dwordx4 v[148:149], v[152:155], off
	v_pk_mul_f32 v[172:173], v[80:81], v[0:1] op_sel_hi:[1,0]
	v_pk_mul_f32 v[156:157], v[132:133], v[156:157]
	v_pk_mul_f32 v[152:153], v[86:87], v[0:1] op_sel_hi:[1,0]
	v_pk_mul_f32 v[154:155], v[88:89], v[0:1] op_sel_hi:[1,0]
	v_pk_mul_f32 v[152:153], v[136:137], v[152:153]
	v_pk_mul_f32 v[154:155], v[134:135], v[154:155]
	v_pk_mul_f32 v[172:173], v[130:131], v[172:173]
	v_cvt_pk_bf16_f32 v152, v152, v153
	v_cvt_pk_bf16_f32 v153, v154, v155
	v_cvt_pk_bf16_f32 v154, v156, v157
	s_nop 0
	v_cvt_pk_bf16_f32 v155, v172, v173
	global_store_dwordx4 v[148:149], v[152:155], off offset:64
	v_or_b32_e32 v148, 48, v170
	v_ashrrev_i32_e32 v149, 31, v148
	v_lshlrev_b64 v[148:149], 11, v[148:149]
	v_lshl_add_u64 v[148:149], v[146:147], 0, v[148:149]
	s_waitcnt vmcnt(2)
	v_pk_add_f32 v[154:155], v[196:197], v[200:201]
	v_pk_add_f32 v[152:153], v[194:195], v[198:199]
	v_pk_add_f32 v[156:157], v[204:205], v[208:209]
	v_pk_add_f32 v[176:177], v[202:203], v[206:207]
	v_add_u32_e32 v226, 0x80, v170
	v_ashrrev_i32_e32 v227, 31, v226
	v_lshlrev_b64 v[226:227], 6, v[226:227]
	v_lshl_add_u64 v[228:229], s[92:93], 0, v[226:227]
	global_load_dwordx4 v[194:197], v[228:229], off offset:32
	global_load_dwordx4 v[198:201], v[228:229], off offset:48
	global_load_dwordx4 v[202:205], v[228:229], off
	global_load_dwordx4 v[206:209], v[228:229], off offset:16
	v_pk_add_f32 v[154:155], v[156:157], v[154:155]
	v_pk_add_f32 v[152:153], v[176:177], v[152:153]
	v_pk_mul_f32 v[174:175], v[68:69], v[68:69]
	v_pk_mov_b32 v[156:157], v[152:153], v[154:155] op_sel:[1,0]
	v_mov_b32_e32 v153, v155
	v_pk_add_f32 v[152:153], v[156:157], v[152:153]
	v_pk_mul_f32 v[154:155], v[82:83], v[82:83]
	v_add_f32_e32 v0, v152, v153
	v_pk_mul_f32 v[152:153], v[84:85], v[84:85]
	v_pk_mul_f32 v[176:177], v[66:67], v[66:67]
	v_pk_mov_b32 v[156:157], v[154:155], v[152:153] op_sel:[1,0]
	v_mov_b32_e32 v155, v153
	v_pk_add_f32 v[152:153], v[156:157], v[154:155]
	v_pk_mul_f32 v[154:155], v[76:77], v[76:77]
	v_pk_mul_f32 v[156:157], v[74:75], v[74:75]
	v_pk_add_f32 v[152:153], v[152:153], v[152:153] op_sel:[0,1] op_sel_hi:[1,0]
	v_pk_mov_b32 v[172:173], v[156:157], v[154:155] op_sel:[1,0]
	v_mov_b32_e32 v157, v155
	v_pk_add_f32 v[154:155], v[172:173], v[156:157]
	v_pk_mul_f32 v[156:157], v[72:73], v[72:73]
	v_pk_add_f32 v[154:155], v[154:155], v[154:155] op_sel:[0,1] op_sel_hi:[1,0]
	v_pk_mul_f32 v[172:173], v[70:71], v[70:71]
	v_add_f32_e32 v156, v156, v157
	v_add_f32_e32 v172, v172, v173
	v_mov_b32_e32 v153, v176
	v_mov_b32_e32 v155, v177
	v_mov_b32_e32 v173, v174
	v_mov_b32_e32 v157, v175
	v_pk_add_f32 v[152:153], v[152:153], v[154:155]
	v_pk_add_f32 v[154:155], v[172:173], v[156:157]
	v_fmamk_f32 v0, v0, 0x3a800000, v211
	v_pk_add_f32 v[152:153], v[152:153], v[154:155]
	v_rsq_f32_e32 v0, v0
	v_add_f32_e32 v152, v152, v153
	ds_bpermute_b32 v153, v150, v152
	s_waitcnt lgkmcnt(0)
	v_add_f32_e32 v152, v152, v153
	ds_bpermute_b32 v153, v151, v152
	s_waitcnt lgkmcnt(0)
	v_add_f32_e32 v152, v152, v153
	v_mul_f32_e32 v152, v152, v0
	v_mul_f32_e32 v152, v0, v152
	v_fmamk_f32 v152, v152, 0x3c800000, v211
	v_rsq_f32_e32 v152, v152
	s_nop 0
	v_mul_f32_e32 v0, v0, v152
	v_pk_mul_f32 v[152:153], v[82:83], v[0:1] op_sel_hi:[1,0]
	v_pk_mul_f32 v[154:155], v[84:85], v[0:1] op_sel_hi:[1,0]
	v_pk_mul_f32 v[152:153], v[144:145], v[152:153]
	v_pk_mul_f32 v[154:155], v[142:143], v[154:155]
	v_pk_mul_f32 v[156:157], v[74:75], v[0:1] op_sel_hi:[1,0]
	v_pk_mul_f32 v[172:173], v[76:77], v[0:1] op_sel_hi:[1,0]
	v_pk_mul_f32 v[156:157], v[140:141], v[156:157]
	v_pk_mul_f32 v[172:173], v[138:139], v[172:173]
	v_cvt_pk_bf16_f32 v152, v152, v153
	v_cvt_pk_bf16_f32 v153, v154, v155
	v_cvt_pk_bf16_f32 v154, v156, v157
	v_pk_mul_f32 v[156:157], v[66:67], v[0:1] op_sel_hi:[1,0]
	v_cvt_pk_bf16_f32 v155, v172, v173
	global_store_dwordx4 v[148:149], v[152:155], off
	v_pk_mul_f32 v[172:173], v[68:69], v[0:1] op_sel_hi:[1,0]
	v_pk_mul_f32 v[156:157], v[132:133], v[156:157]
	v_pk_mul_f32 v[152:153], v[70:71], v[0:1] op_sel_hi:[1,0]
	v_pk_mul_f32 v[154:155], v[72:73], v[0:1] op_sel_hi:[1,0]
	v_pk_mul_f32 v[152:153], v[136:137], v[152:153]
	v_pk_mul_f32 v[154:155], v[134:135], v[154:155]
	v_pk_mul_f32 v[172:173], v[130:131], v[172:173]
	v_cvt_pk_bf16_f32 v152, v152, v153
	v_cvt_pk_bf16_f32 v153, v154, v155
	v_cvt_pk_bf16_f32 v154, v156, v157
	s_nop 0
	v_cvt_pk_bf16_f32 v155, v172, v173
	global_store_dwordx4 v[148:149], v[152:155], off offset:64
	v_add_u32_e32 v148, 0x80, v170
	v_ashrrev_i32_e32 v149, 31, v148
	v_lshlrev_b64 v[148:149], 11, v[148:149]
	v_lshl_add_u64 v[148:149], v[146:147], 0, v[148:149]
	s_waitcnt vmcnt(2)
	v_pk_add_f32 v[154:155], v[196:197], v[200:201]
	v_pk_add_f32 v[152:153], v[194:195], v[198:199]
	v_pk_add_f32 v[156:157], v[204:205], v[208:209]
	v_pk_add_f32 v[176:177], v[202:203], v[206:207]
	v_add_u32_e32 v226, 0x90, v170
	v_ashrrev_i32_e32 v227, 31, v226
	v_lshlrev_b64 v[226:227], 6, v[226:227]
	v_lshl_add_u64 v[228:229], s[92:93], 0, v[226:227]
	global_load_dwordx4 v[194:197], v[228:229], off offset:32
	global_load_dwordx4 v[198:201], v[228:229], off offset:48
	global_load_dwordx4 v[202:205], v[228:229], off
	global_load_dwordx4 v[206:209], v[228:229], off offset:16
	v_pk_add_f32 v[154:155], v[156:157], v[154:155]
	v_pk_add_f32 v[152:153], v[176:177], v[152:153]
	v_pk_mul_f32 v[174:175], v[48:49], v[48:49]
	v_pk_mov_b32 v[156:157], v[152:153], v[154:155] op_sel:[1,0]
	v_mov_b32_e32 v153, v155
	v_pk_add_f32 v[152:153], v[156:157], v[152:153]
	v_pk_mul_f32 v[154:155], v[62:63], v[62:63]
	v_add_f32_e32 v0, v152, v153
	v_pk_mul_f32 v[152:153], v[64:65], v[64:65]
	v_pk_mul_f32 v[176:177], v[46:47], v[46:47]
	v_pk_mov_b32 v[156:157], v[154:155], v[152:153] op_sel:[1,0]
	v_mov_b32_e32 v155, v153
	v_pk_add_f32 v[152:153], v[156:157], v[154:155]
	v_pk_mul_f32 v[154:155], v[60:61], v[60:61]
	v_pk_mul_f32 v[156:157], v[58:59], v[58:59]
	v_pk_add_f32 v[152:153], v[152:153], v[152:153] op_sel:[0,1] op_sel_hi:[1,0]
	v_pk_mov_b32 v[172:173], v[156:157], v[154:155] op_sel:[1,0]
	v_mov_b32_e32 v157, v155
	v_pk_add_f32 v[154:155], v[172:173], v[156:157]
	v_pk_mul_f32 v[156:157], v[56:57], v[56:57]
	v_pk_add_f32 v[154:155], v[154:155], v[154:155] op_sel:[0,1] op_sel_hi:[1,0]
	v_pk_mul_f32 v[172:173], v[54:55], v[54:55]
	v_add_f32_e32 v156, v156, v157
	v_add_f32_e32 v172, v172, v173
	v_mov_b32_e32 v153, v176
	v_mov_b32_e32 v155, v177
	v_mov_b32_e32 v173, v174
	v_mov_b32_e32 v157, v175
	v_pk_add_f32 v[152:153], v[152:153], v[154:155]
	v_pk_add_f32 v[154:155], v[172:173], v[156:157]
	v_fmamk_f32 v0, v0, 0x3a800000, v211
	v_pk_add_f32 v[152:153], v[152:153], v[154:155]
	v_rsq_f32_e32 v0, v0
	v_add_f32_e32 v152, v152, v153
	ds_bpermute_b32 v153, v150, v152
	s_waitcnt lgkmcnt(0)
	v_add_f32_e32 v152, v152, v153
	ds_bpermute_b32 v153, v151, v152
	s_waitcnt lgkmcnt(0)
	v_add_f32_e32 v152, v152, v153
	v_mul_f32_e32 v152, v152, v0
	v_mul_f32_e32 v152, v0, v152
	v_fmamk_f32 v152, v152, 0x3c800000, v211
	v_rsq_f32_e32 v152, v152
	s_nop 0
	v_mul_f32_e32 v0, v0, v152
	v_pk_mul_f32 v[152:153], v[62:63], v[0:1] op_sel_hi:[1,0]
	v_pk_mul_f32 v[154:155], v[64:65], v[0:1] op_sel_hi:[1,0]
	v_pk_mul_f32 v[152:153], v[144:145], v[152:153]
	v_pk_mul_f32 v[154:155], v[142:143], v[154:155]
	v_pk_mul_f32 v[156:157], v[58:59], v[0:1] op_sel_hi:[1,0]
	v_pk_mul_f32 v[172:173], v[60:61], v[0:1] op_sel_hi:[1,0]
	v_pk_mul_f32 v[156:157], v[140:141], v[156:157]
	v_pk_mul_f32 v[172:173], v[138:139], v[172:173]
	v_cvt_pk_bf16_f32 v152, v152, v153
	v_cvt_pk_bf16_f32 v153, v154, v155
	v_cvt_pk_bf16_f32 v154, v156, v157
	v_pk_mul_f32 v[156:157], v[46:47], v[0:1] op_sel_hi:[1,0]
	v_cvt_pk_bf16_f32 v155, v172, v173
	global_store_dwordx4 v[148:149], v[152:155], off
	v_pk_mul_f32 v[172:173], v[48:49], v[0:1] op_sel_hi:[1,0]
	v_pk_mul_f32 v[156:157], v[132:133], v[156:157]
	v_pk_mul_f32 v[152:153], v[54:55], v[0:1] op_sel_hi:[1,0]
	v_pk_mul_f32 v[154:155], v[56:57], v[0:1] op_sel_hi:[1,0]
	v_pk_mul_f32 v[152:153], v[136:137], v[152:153]
	v_pk_mul_f32 v[154:155], v[134:135], v[154:155]
	v_pk_mul_f32 v[172:173], v[130:131], v[172:173]
	v_cvt_pk_bf16_f32 v152, v152, v153
	v_cvt_pk_bf16_f32 v153, v154, v155
	v_cvt_pk_bf16_f32 v154, v156, v157
	s_nop 0
	v_cvt_pk_bf16_f32 v155, v172, v173
	global_store_dwordx4 v[148:149], v[152:155], off offset:64
	v_add_u32_e32 v148, 0x90, v170
	v_ashrrev_i32_e32 v149, 31, v148
	v_lshlrev_b64 v[148:149], 11, v[148:149]
	v_lshl_add_u64 v[148:149], v[146:147], 0, v[148:149]
	s_waitcnt vmcnt(2)
	v_pk_add_f32 v[154:155], v[196:197], v[200:201]
	v_pk_add_f32 v[152:153], v[194:195], v[198:199]
	v_pk_add_f32 v[156:157], v[204:205], v[208:209]
	v_pk_add_f32 v[176:177], v[202:203], v[206:207]
	v_add_u32_e32 v226, 0xa0, v170
	v_ashrrev_i32_e32 v227, 31, v226
	v_lshlrev_b64 v[226:227], 6, v[226:227]
	v_lshl_add_u64 v[228:229], s[92:93], 0, v[226:227]
	global_load_dwordx4 v[194:197], v[228:229], off offset:32
	global_load_dwordx4 v[198:201], v[228:229], off offset:48
	global_load_dwordx4 v[202:205], v[228:229], off
	global_load_dwordx4 v[206:209], v[228:229], off offset:16
	v_pk_add_f32 v[154:155], v[156:157], v[154:155]
	v_pk_add_f32 v[152:153], v[176:177], v[152:153]
	v_pk_mul_f32 v[174:175], v[32:33], v[32:33]
	v_pk_mov_b32 v[156:157], v[152:153], v[154:155] op_sel:[1,0]
	v_mov_b32_e32 v153, v155
	v_pk_add_f32 v[152:153], v[156:157], v[152:153]
	v_pk_mul_f32 v[154:155], v[50:51], v[50:51]
	v_add_f32_e32 v0, v152, v153
	v_pk_mul_f32 v[152:153], v[52:53], v[52:53]
	v_pk_mul_f32 v[176:177], v[30:31], v[30:31]
	v_pk_mov_b32 v[156:157], v[154:155], v[152:153] op_sel:[1,0]
	v_mov_b32_e32 v155, v153
	v_pk_add_f32 v[152:153], v[156:157], v[154:155]
	v_pk_mul_f32 v[154:155], v[44:45], v[44:45]
	v_pk_mul_f32 v[156:157], v[42:43], v[42:43]
	v_pk_add_f32 v[152:153], v[152:153], v[152:153] op_sel:[0,1] op_sel_hi:[1,0]
	v_pk_mov_b32 v[172:173], v[156:157], v[154:155] op_sel:[1,0]
	v_mov_b32_e32 v157, v155
	v_pk_add_f32 v[154:155], v[172:173], v[156:157]
	v_pk_mul_f32 v[156:157], v[40:41], v[40:41]
	v_pk_add_f32 v[154:155], v[154:155], v[154:155] op_sel:[0,1] op_sel_hi:[1,0]
	v_pk_mul_f32 v[172:173], v[38:39], v[38:39]
	v_add_f32_e32 v156, v156, v157
	v_add_f32_e32 v172, v172, v173
	v_mov_b32_e32 v153, v176
	v_mov_b32_e32 v155, v177
	v_mov_b32_e32 v173, v174
	v_mov_b32_e32 v157, v175
	v_pk_add_f32 v[152:153], v[152:153], v[154:155]
	v_pk_add_f32 v[154:155], v[172:173], v[156:157]
	v_fmamk_f32 v0, v0, 0x3a800000, v211
	v_pk_add_f32 v[152:153], v[152:153], v[154:155]
	v_rsq_f32_e32 v0, v0
	v_add_f32_e32 v152, v152, v153
	ds_bpermute_b32 v153, v150, v152
	s_waitcnt lgkmcnt(0)
	v_add_f32_e32 v152, v152, v153
	ds_bpermute_b32 v153, v151, v152
	s_waitcnt lgkmcnt(0)
	v_add_f32_e32 v152, v152, v153
	v_mul_f32_e32 v152, v152, v0
	v_mul_f32_e32 v152, v0, v152
	v_fmamk_f32 v152, v152, 0x3c800000, v211
	v_rsq_f32_e32 v152, v152
	s_nop 0
	v_mul_f32_e32 v0, v0, v152
	v_pk_mul_f32 v[152:153], v[50:51], v[0:1] op_sel_hi:[1,0]
	v_pk_mul_f32 v[154:155], v[52:53], v[0:1] op_sel_hi:[1,0]
	v_pk_mul_f32 v[152:153], v[144:145], v[152:153]
	v_pk_mul_f32 v[154:155], v[142:143], v[154:155]
	v_pk_mul_f32 v[156:157], v[42:43], v[0:1] op_sel_hi:[1,0]
	v_pk_mul_f32 v[172:173], v[44:45], v[0:1] op_sel_hi:[1,0]
	v_pk_mul_f32 v[156:157], v[140:141], v[156:157]
	v_pk_mul_f32 v[172:173], v[138:139], v[172:173]
	v_cvt_pk_bf16_f32 v152, v152, v153
	v_cvt_pk_bf16_f32 v153, v154, v155
	v_cvt_pk_bf16_f32 v154, v156, v157
	v_pk_mul_f32 v[156:157], v[30:31], v[0:1] op_sel_hi:[1,0]
	v_cvt_pk_bf16_f32 v155, v172, v173
	global_store_dwordx4 v[148:149], v[152:155], off
	v_pk_mul_f32 v[172:173], v[32:33], v[0:1] op_sel_hi:[1,0]
	v_pk_mul_f32 v[156:157], v[132:133], v[156:157]
	v_pk_mul_f32 v[152:153], v[38:39], v[0:1] op_sel_hi:[1,0]
	v_pk_mul_f32 v[154:155], v[40:41], v[0:1] op_sel_hi:[1,0]
	v_pk_mul_f32 v[152:153], v[136:137], v[152:153]
	v_pk_mul_f32 v[154:155], v[134:135], v[154:155]
	v_pk_mul_f32 v[172:173], v[130:131], v[172:173]
	v_cvt_pk_bf16_f32 v152, v152, v153
	v_cvt_pk_bf16_f32 v153, v154, v155
	v_cvt_pk_bf16_f32 v154, v156, v157
	s_nop 0
	v_cvt_pk_bf16_f32 v155, v172, v173
	global_store_dwordx4 v[148:149], v[152:155], off offset:64
	v_add_u32_e32 v148, 0xa0, v170
	v_ashrrev_i32_e32 v149, 31, v148
	v_lshlrev_b64 v[148:149], 11, v[148:149]
	v_lshl_add_u64 v[148:149], v[146:147], 0, v[148:149]
	s_waitcnt vmcnt(2)
	v_pk_add_f32 v[154:155], v[196:197], v[200:201]
	v_pk_add_f32 v[152:153], v[194:195], v[198:199]
	v_pk_add_f32 v[156:157], v[204:205], v[208:209]
	v_pk_add_f32 v[176:177], v[202:203], v[206:207]
	v_pk_add_f32 v[154:155], v[156:157], v[154:155]
	v_pk_add_f32 v[152:153], v[176:177], v[152:153]
	v_pk_mul_f32 v[174:175], v[16:17], v[16:17]
	v_pk_mov_b32 v[156:157], v[152:153], v[154:155] op_sel:[1,0]
	v_mov_b32_e32 v153, v155
	v_pk_add_f32 v[152:153], v[156:157], v[152:153]
	v_pk_mul_f32 v[154:155], v[34:35], v[34:35]
	v_add_f32_e32 v0, v152, v153
	v_pk_mul_f32 v[152:153], v[36:37], v[36:37]
	v_pk_mul_f32 v[176:177], v[14:15], v[14:15]
	v_pk_mov_b32 v[156:157], v[154:155], v[152:153] op_sel:[1,0]
	v_mov_b32_e32 v155, v153
	v_pk_add_f32 v[152:153], v[156:157], v[154:155]
	v_pk_mul_f32 v[154:155], v[28:29], v[28:29]
	v_pk_mul_f32 v[156:157], v[26:27], v[26:27]
	v_pk_add_f32 v[152:153], v[152:153], v[152:153] op_sel:[0,1] op_sel_hi:[1,0]
	v_pk_mov_b32 v[172:173], v[156:157], v[154:155] op_sel:[1,0]
	v_mov_b32_e32 v157, v155
	v_pk_add_f32 v[154:155], v[172:173], v[156:157]
	v_pk_mul_f32 v[156:157], v[24:25], v[24:25]
	v_pk_add_f32 v[154:155], v[154:155], v[154:155] op_sel:[0,1] op_sel_hi:[1,0]
	v_pk_mul_f32 v[172:173], v[22:23], v[22:23]
	v_add_f32_e32 v156, v156, v157
	v_add_f32_e32 v172, v172, v173
	v_mov_b32_e32 v153, v176
	v_mov_b32_e32 v155, v177
	v_mov_b32_e32 v173, v174
	v_mov_b32_e32 v157, v175
	v_pk_add_f32 v[152:153], v[152:153], v[154:155]
	v_pk_add_f32 v[154:155], v[172:173], v[156:157]
	v_fmamk_f32 v0, v0, 0x3a800000, v211
	v_pk_add_f32 v[152:153], v[152:153], v[154:155]
	v_rsq_f32_e32 v0, v0
	v_add_f32_e32 v152, v152, v153
	ds_bpermute_b32 v153, v150, v152
	s_waitcnt lgkmcnt(0)
	v_add_f32_e32 v152, v152, v153
	ds_bpermute_b32 v153, v151, v152
	s_waitcnt lgkmcnt(0)
	v_add_f32_e32 v152, v152, v153
	v_mul_f32_e32 v152, v152, v0
	v_mul_f32_e32 v152, v0, v152
	v_fmamk_f32 v152, v152, 0x3c800000, v211
	v_rsq_f32_e32 v152, v152
	s_nop 0
	v_mul_f32_e32 v0, v0, v152
	v_pk_mul_f32 v[152:153], v[34:35], v[0:1] op_sel_hi:[1,0]
	v_pk_mul_f32 v[154:155], v[36:37], v[0:1] op_sel_hi:[1,0]
	v_pk_mul_f32 v[152:153], v[144:145], v[152:153]
	v_pk_mul_f32 v[154:155], v[142:143], v[154:155]
	v_pk_mul_f32 v[156:157], v[26:27], v[0:1] op_sel_hi:[1,0]
	v_pk_mul_f32 v[172:173], v[28:29], v[0:1] op_sel_hi:[1,0]
	v_pk_mul_f32 v[156:157], v[140:141], v[156:157]
	v_pk_mul_f32 v[172:173], v[138:139], v[172:173]
	v_cvt_pk_bf16_f32 v152, v152, v153
	v_cvt_pk_bf16_f32 v153, v154, v155
	v_cvt_pk_bf16_f32 v154, v156, v157
	v_pk_mul_f32 v[156:157], v[14:15], v[0:1] op_sel_hi:[1,0]
	v_cvt_pk_bf16_f32 v155, v172, v173
	global_store_dwordx4 v[148:149], v[152:155], off
	v_pk_mul_f32 v[172:173], v[16:17], v[0:1] op_sel_hi:[1,0]
	v_pk_mul_f32 v[156:157], v[132:133], v[156:157]
	v_pk_mul_f32 v[152:153], v[22:23], v[0:1] op_sel_hi:[1,0]
	v_pk_mul_f32 v[154:155], v[24:25], v[0:1] op_sel_hi:[1,0]
	v_pk_mul_f32 v[152:153], v[136:137], v[152:153]
	v_pk_mul_f32 v[154:155], v[134:135], v[154:155]
	v_pk_mul_f32 v[172:173], v[130:131], v[172:173]
	v_cvt_pk_bf16_f32 v152, v152, v153
	v_cvt_pk_bf16_f32 v153, v154, v155
	v_cvt_pk_bf16_f32 v154, v156, v157
	s_nop 0
	v_cvt_pk_bf16_f32 v155, v172, v173
	global_store_dwordx4 v[148:149], v[152:155], off offset:64
	v_add_u32_e32 v148, 0xb0, v170
	v_ashrrev_i32_e32 v149, 31, v148
	v_lshlrev_b64 v[152:153], 6, v[148:149]
	v_lshl_add_u64 v[156:157], s[92:93], 0, v[152:153]
	global_load_dwordx4 v[152:155], v[156:157], off offset:32
	global_load_dwordx4 v[172:175], v[156:157], off offset:48
	global_load_dwordx4 v[186:189], v[156:157], off
	global_load_dwordx4 v[190:193], v[156:157], off offset:16
	v_lshlrev_b64 v[148:149], 11, v[148:149]
	v_lshl_add_u64 v[146:147], v[146:147], 0, v[148:149]
	s_waitcnt vmcnt(2)
	v_pk_add_f32 v[154:155], v[154:155], v[174:175]
	v_pk_add_f32 v[152:153], v[152:153], v[172:173]
	s_waitcnt vmcnt(0)
	v_pk_add_f32 v[156:157], v[188:189], v[192:193]
	v_pk_add_f32 v[176:177], v[186:187], v[190:191]
	v_pk_add_f32 v[154:155], v[156:157], v[154:155]
	v_pk_add_f32 v[152:153], v[176:177], v[152:153]
	v_pk_mul_f32 v[174:175], v[4:5], v[4:5]
	v_pk_mov_b32 v[156:157], v[152:153], v[154:155] op_sel:[1,0]
	v_mov_b32_e32 v153, v155
	v_pk_add_f32 v[152:153], v[156:157], v[152:153]
	v_pk_mul_f32 v[154:155], v[18:19], v[18:19]
	v_add_f32_e32 v0, v152, v153
	v_pk_mul_f32 v[152:153], v[20:21], v[20:21]
	v_pk_mul_f32 v[176:177], v[2:3], v[2:3]
	v_pk_mov_b32 v[156:157], v[154:155], v[152:153] op_sel:[1,0]
	v_mov_b32_e32 v155, v153
	v_pk_add_f32 v[152:153], v[156:157], v[154:155]
	v_pk_mul_f32 v[154:155], v[12:13], v[12:13]
	v_pk_mul_f32 v[156:157], v[10:11], v[10:11]
	v_pk_add_f32 v[152:153], v[152:153], v[152:153] op_sel:[0,1] op_sel_hi:[1,0]
	v_pk_mov_b32 v[172:173], v[156:157], v[154:155] op_sel:[1,0]
	v_mov_b32_e32 v157, v155
	v_pk_add_f32 v[154:155], v[172:173], v[156:157]
	v_pk_mul_f32 v[156:157], v[8:9], v[8:9]
	v_pk_add_f32 v[154:155], v[154:155], v[154:155] op_sel:[0,1] op_sel_hi:[1,0]
	v_pk_mul_f32 v[172:173], v[6:7], v[6:7]
	v_add_f32_e32 v156, v156, v157
	v_add_f32_e32 v172, v172, v173
	v_mov_b32_e32 v153, v176
	v_mov_b32_e32 v155, v177
	v_mov_b32_e32 v173, v174
	v_mov_b32_e32 v157, v175
	v_pk_add_f32 v[152:153], v[152:153], v[154:155]
	v_pk_add_f32 v[154:155], v[172:173], v[156:157]
	v_fmamk_f32 v0, v0, 0x3a800000, v211
	v_pk_add_f32 v[152:153], v[152:153], v[154:155]
	v_rsq_f32_e32 v0, v0
	v_add_f32_e32 v152, v152, v153
	ds_bpermute_b32 v150, v150, v152
	s_waitcnt lgkmcnt(0)
	v_add_f32_e32 v150, v152, v150
	ds_bpermute_b32 v151, v151, v150
	s_waitcnt lgkmcnt(0)
	v_add_f32_e32 v150, v150, v151
	v_mul_f32_e32 v150, v150, v0
	v_mul_f32_e32 v150, v0, v150
	v_fmamk_f32 v150, v150, 0x3c800000, v211
	v_rsq_f32_e32 v150, v150
	s_nop 0
	v_mul_f32_e32 v0, v0, v150
	v_pk_mul_f32 v[148:149], v[18:19], v[0:1] op_sel_hi:[1,0]
	v_pk_mul_f32 v[150:151], v[20:21], v[0:1] op_sel_hi:[1,0]
	v_pk_mul_f32 v[144:145], v[144:145], v[148:149]
	v_pk_mul_f32 v[142:143], v[142:143], v[150:151]
	v_pk_mul_f32 v[148:149], v[10:11], v[0:1] op_sel_hi:[1,0]
	v_pk_mul_f32 v[150:151], v[12:13], v[0:1] op_sel_hi:[1,0]
	v_pk_mul_f32 v[140:141], v[140:141], v[148:149]
	v_pk_mul_f32 v[150:151], v[138:139], v[150:151]
	v_cvt_pk_bf16_f32 v138, v144, v145
	v_cvt_pk_bf16_f32 v139, v142, v143
	v_cvt_pk_bf16_f32 v140, v140, v141
	s_nop 0
	v_cvt_pk_bf16_f32 v141, v150, v151
	global_store_dwordx4 v[146:147], v[138:141], off
	s_nop 1
	v_pk_mul_f32 v[138:139], v[6:7], v[0:1] op_sel_hi:[1,0]
	v_pk_mul_f32 v[140:141], v[8:9], v[0:1] op_sel_hi:[1,0]
	v_pk_mul_f32 v[136:137], v[136:137], v[138:139]
	v_pk_mul_f32 v[138:139], v[2:3], v[0:1] op_sel_hi:[1,0]
	v_pk_mul_f32 v[134:135], v[134:135], v[140:141]
	v_pk_mul_f32 v[140:141], v[4:5], v[0:1] op_sel_hi:[1,0]
	v_pk_mul_f32 v[132:133], v[132:133], v[138:139]
	v_pk_mul_f32 v[140:141], v[130:131], v[140:141]
	v_cvt_pk_bf16_f32 v130, v136, v137
	v_cvt_pk_bf16_f32 v131, v134, v135
	v_cvt_pk_bf16_f32 v132, v132, v133
	s_nop 0
	v_cvt_pk_bf16_f32 v133, v140, v141
	global_store_dwordx4 v[146:147], v[130:133], off offset:64
